# all GEMM K-loops: peeled first iteration whose first MFMA per accumulator takes C=0 (accumulator zeroing block removed)
# speedup vs baseline: 1.0270x; 1.0041x over previous
.LBB0_251:
	s_ashr_i32 s13, s12, 31
	s_lshl_b64 s[14:15], s[12:13], 19
	s_add_u32 s14, s29, s14
	s_addc_u32 s15, s38, s15
	s_and_b64 s[16:17], s[4:5], exec
	s_cselect_b32 s13, s15, s23
	s_cselect_b32 s19, s14, s22
	s_ashr_i32 s11, s10, 31
	s_lshl_b64 s[16:17], s[10:11], 19
	s_add_u32 s16, s39, s16
	s_addc_u32 s17, s40, s17
	s_and_b64 s[24:25], s[4:5], exec
	s_cselect_b32 s11, s17, s21
	s_cselect_b32 s61, s16, s20
	s_add_u32 s62, s20, 0x100
	s_addc_u32 s63, s21, 0
	s_add_u32 s20, s22, 0x40080
	s_addc_u32 s21, s23, 0
	s_mov_b32 s68, -2
	s_add_u32 s22, s20, 0xfffc0080
	s_addc_u32 s23, s21, -1
	s_add_i32 s64, 0, 0x10000
	s_cmp_eq_u32 s68, 12
	s_cselect_b32 s25, s13, s23
	s_cselect_b32 s24, s19, s22
	s_cselect_b32 s23, s11, s63
	s_cselect_b32 s22, s61, s62
	s_add_i32 s69, 0, 0x14000
	v_add_u32_e32 v140, s64, v167
	v_add_u32_e32 v164, s69, v167
	ds_read_b128 v[48:51], v140
	ds_read_b128 v[56:59], v140 offset:1024
	ds_read_b128 v[136:139], v140 offset:2048
	ds_read_b128 v[140:143], v140 offset:3072
	ds_read_b128 v[156:159], v164
	ds_read_b128 v[160:163], v164 offset:1024
	ds_read_b128 v[182:185], v164 offset:2048
	ds_read_b128 v[186:189], v164 offset:3072
	v_lshl_add_u64 v[164:165], s[20:21], 0, v[154:155]
	s_add_i32 m0, s49, 0xc000
	ds_read_b128 v[190:193], v172
	ds_read_b128 v[194:197], v172 offset:1024
	ds_read_b128 v[198:201], v172 offset:2048
	ds_read_b128 v[202:205], v172 offset:3072
	ds_read_b128 v[206:209], v172 offset:4096
	ds_read_b128 v[210:213], v172 offset:5120
	ds_read_b128 v[228:231], v172 offset:6144
	ds_read_b128 v[232:235], v172 offset:7168
	global_load_lds_dwordx4 v[164:165], off
	v_lshl_add_u64 v[164:165], s[20:21], 0, v[152:153]
	s_add_i32 m0, s49, 0xe000
	s_nop 0
	global_load_lds_dwordx4 v[164:165], off
	s_waitcnt vmcnt(8)
	s_waitcnt lgkmcnt(0)
	s_barrier
	s_setprio 1
	v_mfma_f32_16x16x32_bf16 v[132:135], v[48:51], v[190:193], 0
	v_mfma_f32_16x16x32_bf16 v[124:127], v[136:139], v[190:193], 0
	v_mfma_f32_16x16x32_bf16 v[116:119], v[48:51], v[198:201], 0
	v_mfma_f32_16x16x32_bf16 v[112:115], v[136:139], v[198:201], 0
	v_mfma_f32_16x16x32_bf16 v[100:103], v[48:51], v[206:209], 0
	v_mfma_f32_16x16x32_bf16 v[96:99], v[136:139], v[206:209], 0
	v_mfma_f32_16x16x32_bf16 v[84:87], v[48:51], v[228:231], 0
	v_mfma_f32_16x16x32_bf16 v[80:83], v[136:139], v[228:231], 0
	v_mfma_f32_16x16x32_bf16 v[132:135], v[56:59], v[194:197], v[132:135]
	v_mfma_f32_16x16x32_bf16 v[124:127], v[140:143], v[194:197], v[124:127]
	v_mfma_f32_16x16x32_bf16 v[116:119], v[56:59], v[202:205], v[116:119]
	v_mfma_f32_16x16x32_bf16 v[112:115], v[140:143], v[202:205], v[112:115]
	v_mfma_f32_16x16x32_bf16 v[100:103], v[56:59], v[210:213], v[100:103]
	v_mfma_f32_16x16x32_bf16 v[96:99], v[140:143], v[210:213], v[96:99]
	v_mfma_f32_16x16x32_bf16 v[84:87], v[56:59], v[232:235], v[84:87]
	v_mfma_f32_16x16x32_bf16 v[80:83], v[140:143], v[232:235], v[80:83]
	v_mfma_f32_16x16x32_bf16 v[128:131], v[156:159], v[190:193], 0
	v_mfma_f32_16x16x32_bf16 v[120:123], v[182:185], v[190:193], 0
	v_mfma_f32_16x16x32_bf16 v[108:111], v[156:159], v[198:201], 0
	v_mfma_f32_16x16x32_bf16 v[104:107], v[182:185], v[198:201], 0
	v_mfma_f32_16x16x32_bf16 v[92:95], v[156:159], v[206:209], 0
	v_mfma_f32_16x16x32_bf16 v[88:91], v[182:185], v[206:209], 0
	v_mfma_f32_16x16x32_bf16 v[76:79], v[156:159], v[228:231], 0
	v_mfma_f32_16x16x32_bf16 v[72:75], v[182:185], v[228:231], 0
	v_mfma_f32_16x16x32_bf16 v[128:131], v[160:163], v[194:197], v[128:131]
	v_mfma_f32_16x16x32_bf16 v[120:123], v[186:189], v[194:197], v[120:123]
	v_mfma_f32_16x16x32_bf16 v[108:111], v[160:163], v[202:205], v[108:111]
	v_mfma_f32_16x16x32_bf16 v[104:107], v[186:189], v[202:205], v[104:107]
	s_setprio 2
	s_barrier
	v_mfma_f32_16x16x32_bf16 v[92:95], v[160:163], v[210:213], v[92:95]
	v_mfma_f32_16x16x32_bf16 v[88:91], v[186:189], v[210:213], v[88:91]
	v_mfma_f32_16x16x32_bf16 v[76:79], v[160:163], v[232:235], v[76:79]
	v_mfma_f32_16x16x32_bf16 v[72:75], v[186:189], v[232:235], v[72:75]
	s_setprio 0
	s_add_i32 s64, s64, s41
	v_lshl_add_u64 v[164:165], s[22:23], 0, v[148:149]
	s_mov_b32 m0, s64
	ds_read_b128 v[190:193], v172 offset:16384
	ds_read_b128 v[194:197], v172 offset:17408
	ds_read_b128 v[198:201], v172 offset:18432
	ds_read_b128 v[202:205], v172 offset:19456
	ds_read_b128 v[206:209], v172 offset:20480
	ds_read_b128 v[210:213], v172 offset:21504
	ds_read_b128 v[228:231], v172 offset:22528
	ds_read_b128 v[232:235], v172 offset:23552
	global_load_lds_dwordx4 v[164:165], off
	s_add_i32 m0, s64, 0x2000
	s_add_u32 s64, s22, 0x40000
	v_lshl_add_u64 v[220:221], s[22:23], 0, v[144:145]
	s_addc_u32 s65, s23, 0
	s_add_i32 s69, s69, s41
	global_load_lds_dwordx4 v[220:221], off
	v_lshl_add_u64 v[222:223], s[64:65], 0, v[148:149]
	s_mov_b32 m0, s69
	v_lshl_add_u64 v[226:227], s[24:25], 0, v[146:147]
	global_load_lds_dwordx4 v[222:223], off
	v_lshl_add_u64 v[222:223], s[64:65], 0, v[144:145]
	s_add_i32 m0, s69, 0x2000
	s_nop 0
	global_load_lds_dwordx4 v[222:223], off
	v_lshl_add_u64 v[222:223], s[24:25], 0, v[150:151]
	s_mov_b32 m0, s49
	s_nop 0
	global_load_lds_dwordx4 v[222:223], off
	s_mov_b32 m0, s50
	s_nop 0
	global_load_lds_dwordx4 v[226:227], off
	s_waitcnt vmcnt(8)
	s_waitcnt lgkmcnt(0)
	s_barrier
	s_setprio 1
	v_mfma_f32_16x16x32_bf16 v[68:71], v[48:51], v[190:193], 0
	v_mfma_f32_16x16x32_bf16 v[64:67], v[136:139], v[190:193], 0
	v_mfma_f32_16x16x32_bf16 v[44:47], v[48:51], v[198:201], 0
	v_mfma_f32_16x16x32_bf16 v[40:43], v[136:139], v[198:201], 0
	v_mfma_f32_16x16x32_bf16 v[28:31], v[48:51], v[206:209], 0
	v_mfma_f32_16x16x32_bf16 v[24:27], v[136:139], v[206:209], 0
	v_mfma_f32_16x16x32_bf16 v[12:15], v[48:51], v[228:231], 0
	v_mfma_f32_16x16x32_bf16 v[8:11], v[136:139], v[228:231], 0
	v_mfma_f32_16x16x32_bf16 v[68:71], v[56:59], v[194:197], v[68:71]
	v_mfma_f32_16x16x32_bf16 v[64:67], v[140:143], v[194:197], v[64:67]
	v_mfma_f32_16x16x32_bf16 v[44:47], v[56:59], v[202:205], v[44:47]
	v_mfma_f32_16x16x32_bf16 v[40:43], v[140:143], v[202:205], v[40:43]
	v_mfma_f32_16x16x32_bf16 v[28:31], v[56:59], v[210:213], v[28:31]
	v_mfma_f32_16x16x32_bf16 v[24:27], v[140:143], v[210:213], v[24:27]
	v_mfma_f32_16x16x32_bf16 v[12:15], v[56:59], v[232:235], v[12:15]
	v_mfma_f32_16x16x32_bf16 v[8:11], v[140:143], v[232:235], v[8:11]
	v_mfma_f32_16x16x32_bf16 v[52:55], v[182:185], v[190:193], 0
	v_mfma_f32_16x16x32_bf16 v[36:39], v[156:159], v[198:201], 0
	v_mfma_f32_16x16x32_bf16 v[32:35], v[182:185], v[198:201], 0
	v_mfma_f32_16x16x32_bf16 v[20:23], v[156:159], v[206:209], 0
	v_mfma_f32_16x16x32_bf16 v[16:19], v[182:185], v[206:209], 0
	v_mfma_f32_16x16x32_bf16 v[4:7], v[156:159], v[228:231], 0
	v_mfma_f32_16x16x32_bf16 v[0:3], v[182:185], v[228:231], 0
	v_mfma_f32_16x16x32_bf16 v[48:51], v[156:159], v[190:193], 0
	v_mfma_f32_16x16x32_bf16 v[52:55], v[186:189], v[194:197], v[52:55]
	v_mfma_f32_16x16x32_bf16 v[36:39], v[160:163], v[202:205], v[36:39]
	v_mfma_f32_16x16x32_bf16 v[32:35], v[186:189], v[202:205], v[32:35]
	v_mfma_f32_16x16x32_bf16 v[20:23], v[160:163], v[210:213], v[20:23]
	s_setprio 2
	s_barrier
	v_mfma_f32_16x16x32_bf16 v[16:19], v[186:189], v[210:213], v[16:19]
	v_mfma_f32_16x16x32_bf16 v[4:7], v[160:163], v[232:235], v[4:7]
	v_mfma_f32_16x16x32_bf16 v[0:3], v[186:189], v[232:235], v[0:3]
	v_mfma_f32_16x16x32_bf16 v[48:51], v[160:163], v[194:197], v[48:51]
	s_setprio 0
	s_add_i32 s64, 0, 0x18000
	s_add_i32 s65, 0, 0x1c000
	v_add_u32_e32 v140, s64, v167
	v_add_u32_e32 v173, s65, v167
	ds_read_b128 v[56:59], v140
	ds_read_b128 v[60:63], v140 offset:1024
	ds_read_b128 v[136:139], v140 offset:2048
	ds_read_b128 v[140:143], v140 offset:3072
	ds_read_b128 v[156:159], v173
	ds_read_b128 v[160:163], v173 offset:1024
	ds_read_b128 v[182:185], v173 offset:2048
	ds_read_b128 v[186:189], v173 offset:3072
	s_add_u32 s24, s24, 0x40000
	s_addc_u32 s25, s25, 0
	s_mov_b32 m0, s51
	v_lshl_add_u64 v[236:237], s[24:25], 0, v[150:151]
	ds_read_b128 v[190:193], v172 offset:32768
	ds_read_b128 v[194:197], v172 offset:33792
	ds_read_b128 v[198:201], v172 offset:34816
	ds_read_b128 v[202:205], v172 offset:35840
	ds_read_b128 v[206:209], v172 offset:36864
	ds_read_b128 v[210:213], v172 offset:37888
	ds_read_b128 v[228:231], v172 offset:38912
	ds_read_b128 v[232:235], v172 offset:39936
	global_load_lds_dwordx4 v[236:237], off
	v_lshl_add_u64 v[236:237], s[24:25], 0, v[146:147]
	s_mov_b32 m0, s52
	s_nop 0
	global_load_lds_dwordx4 v[236:237], off
	s_waitcnt vmcnt(8)
	s_waitcnt lgkmcnt(0)
	s_barrier
	s_setprio 1
	v_mfma_f32_16x16x32_bf16 v[132:135], v[56:59], v[190:193], v[132:135]
	v_mfma_f32_16x16x32_bf16 v[124:127], v[136:139], v[190:193], v[124:127]
	v_mfma_f32_16x16x32_bf16 v[116:119], v[56:59], v[198:201], v[116:119]
	v_mfma_f32_16x16x32_bf16 v[112:115], v[136:139], v[198:201], v[112:115]
	v_mfma_f32_16x16x32_bf16 v[100:103], v[56:59], v[206:209], v[100:103]
	v_mfma_f32_16x16x32_bf16 v[96:99], v[136:139], v[206:209], v[96:99]
	v_mfma_f32_16x16x32_bf16 v[84:87], v[56:59], v[228:231], v[84:87]
	v_mfma_f32_16x16x32_bf16 v[80:83], v[136:139], v[228:231], v[80:83]
	v_mfma_f32_16x16x32_bf16 v[132:135], v[60:63], v[194:197], v[132:135]
	v_mfma_f32_16x16x32_bf16 v[124:127], v[140:143], v[194:197], v[124:127]
	v_mfma_f32_16x16x32_bf16 v[116:119], v[60:63], v[202:205], v[116:119]
	v_mfma_f32_16x16x32_bf16 v[112:115], v[140:143], v[202:205], v[112:115]
	v_mfma_f32_16x16x32_bf16 v[100:103], v[60:63], v[210:213], v[100:103]
	v_mfma_f32_16x16x32_bf16 v[96:99], v[140:143], v[210:213], v[96:99]
	v_mfma_f32_16x16x32_bf16 v[84:87], v[60:63], v[232:235], v[84:87]
	v_mfma_f32_16x16x32_bf16 v[80:83], v[140:143], v[232:235], v[80:83]
	v_mfma_f32_16x16x32_bf16 v[128:131], v[156:159], v[190:193], v[128:131]
	v_mfma_f32_16x16x32_bf16 v[120:123], v[182:185], v[190:193], v[120:123]
	v_mfma_f32_16x16x32_bf16 v[108:111], v[156:159], v[198:201], v[108:111]
	v_mfma_f32_16x16x32_bf16 v[104:107], v[182:185], v[198:201], v[104:107]
	v_mfma_f32_16x16x32_bf16 v[92:95], v[156:159], v[206:209], v[92:95]
	v_mfma_f32_16x16x32_bf16 v[88:91], v[182:185], v[206:209], v[88:91]
	v_mfma_f32_16x16x32_bf16 v[76:79], v[156:159], v[228:231], v[76:79]
	v_mfma_f32_16x16x32_bf16 v[72:75], v[182:185], v[228:231], v[72:75]
	v_mfma_f32_16x16x32_bf16 v[128:131], v[160:163], v[194:197], v[128:131]
	v_mfma_f32_16x16x32_bf16 v[120:123], v[186:189], v[194:197], v[120:123]
	v_mfma_f32_16x16x32_bf16 v[108:111], v[160:163], v[202:205], v[108:111]
	v_mfma_f32_16x16x32_bf16 v[104:107], v[186:189], v[202:205], v[104:107]
	s_setprio 2
	s_barrier
	v_mfma_f32_16x16x32_bf16 v[92:95], v[160:163], v[210:213], v[92:95]
	v_mfma_f32_16x16x32_bf16 v[88:91], v[186:189], v[210:213], v[88:91]
	v_mfma_f32_16x16x32_bf16 v[76:79], v[160:163], v[232:235], v[76:79]
	v_mfma_f32_16x16x32_bf16 v[72:75], v[186:189], v[232:235], v[72:75]
	s_setprio 0
	s_add_i32 s24, s64, s41
	v_lshl_add_u64 v[164:165], v[164:165], 0, s[34:35]
	s_mov_b32 m0, s24
	ds_read_b128 v[190:193], v172 offset:49152
	ds_read_b128 v[194:197], v172 offset:50176
	ds_read_b128 v[198:201], v172 offset:51200
	ds_read_b128 v[202:205], v172 offset:52224
	ds_read_b128 v[206:209], v172 offset:53248
	ds_read_b128 v[210:213], v172 offset:54272
	ds_read_b128 v[228:231], v172 offset:55296
	ds_read_b128 v[232:235], v172 offset:56320
	global_load_lds_dwordx4 v[164:165], off
	s_add_i32 m0, s24, 0x2000
	s_add_u32 s22, s22, 0x40080
	v_lshl_add_u64 v[164:165], v[220:221], 0, s[34:35]
	s_addc_u32 s23, s23, 0
	s_add_i32 s24, s65, s41
	global_load_lds_dwordx4 v[164:165], off
	v_lshl_add_u64 v[164:165], s[22:23], 0, v[148:149]
	s_mov_b32 m0, s24
	s_nop 0
	global_load_lds_dwordx4 v[164:165], off
	v_lshl_add_u64 v[164:165], s[22:23], 0, v[144:145]
	s_add_i32 m0, s24, 0x2000
	s_nop 0
	global_load_lds_dwordx4 v[164:165], off
	v_lshl_add_u64 v[164:165], v[222:223], 0, s[34:35]
	s_mov_b32 m0, s55
	s_nop 0
	global_load_lds_dwordx4 v[164:165], off
	v_lshl_add_u64 v[164:165], v[226:227], 0, s[34:35]
	s_mov_b32 m0, s56
	s_nop 0
	global_load_lds_dwordx4 v[164:165], off
	s_waitcnt vmcnt(8)
	s_waitcnt lgkmcnt(0)
	s_barrier
	s_setprio 1
	v_mfma_f32_16x16x32_bf16 v[68:71], v[56:59], v[190:193], v[68:71]
	v_mfma_f32_16x16x32_bf16 v[64:67], v[136:139], v[190:193], v[64:67]
	v_mfma_f32_16x16x32_bf16 v[44:47], v[56:59], v[198:201], v[44:47]
	v_mfma_f32_16x16x32_bf16 v[40:43], v[136:139], v[198:201], v[40:43]
	v_mfma_f32_16x16x32_bf16 v[28:31], v[56:59], v[206:209], v[28:31]
	v_mfma_f32_16x16x32_bf16 v[24:27], v[136:139], v[206:209], v[24:27]
	v_mfma_f32_16x16x32_bf16 v[12:15], v[56:59], v[228:231], v[12:15]
	v_mfma_f32_16x16x32_bf16 v[8:11], v[136:139], v[228:231], v[8:11]
	v_mfma_f32_16x16x32_bf16 v[68:71], v[60:63], v[194:197], v[68:71]
	v_mfma_f32_16x16x32_bf16 v[64:67], v[140:143], v[194:197], v[64:67]
	v_mfma_f32_16x16x32_bf16 v[44:47], v[60:63], v[202:205], v[44:47]
	v_mfma_f32_16x16x32_bf16 v[40:43], v[140:143], v[202:205], v[40:43]
	v_mfma_f32_16x16x32_bf16 v[28:31], v[60:63], v[210:213], v[28:31]
	v_mfma_f32_16x16x32_bf16 v[24:27], v[140:143], v[210:213], v[24:27]
	v_mfma_f32_16x16x32_bf16 v[12:15], v[60:63], v[232:235], v[12:15]
	v_mfma_f32_16x16x32_bf16 v[8:11], v[140:143], v[232:235], v[8:11]
	v_mfma_f32_16x16x32_bf16 v[48:51], v[156:159], v[190:193], v[48:51]
	v_mfma_f32_16x16x32_bf16 v[60:63], v[160:163], v[194:197], v[48:51]
	v_mfma_f32_16x16x32_bf16 v[48:51], v[182:185], v[190:193], v[52:55]
	v_mfma_f32_16x16x32_bf16 v[36:39], v[156:159], v[198:201], v[36:39]
	v_mfma_f32_16x16x32_bf16 v[32:35], v[182:185], v[198:201], v[32:35]
	v_mfma_f32_16x16x32_bf16 v[20:23], v[156:159], v[206:209], v[20:23]
	v_mfma_f32_16x16x32_bf16 v[16:19], v[182:185], v[206:209], v[16:19]
	v_mfma_f32_16x16x32_bf16 v[4:7], v[156:159], v[228:231], v[4:7]
	v_mfma_f32_16x16x32_bf16 v[0:3], v[182:185], v[228:231], v[0:3]
	v_mfma_f32_16x16x32_bf16 v[52:55], v[186:189], v[194:197], v[48:51]
	v_mfma_f32_16x16x32_bf16 v[36:39], v[160:163], v[202:205], v[36:39]
	v_mfma_f32_16x16x32_bf16 v[32:35], v[186:189], v[202:205], v[32:35]
	s_setprio 2
	s_barrier
	v_mfma_f32_16x16x32_bf16 v[20:23], v[160:163], v[210:213], v[20:23]
	v_mfma_f32_16x16x32_bf16 v[16:19], v[186:189], v[210:213], v[16:19]
	v_mfma_f32_16x16x32_bf16 v[4:7], v[160:163], v[232:235], v[4:7]
	v_mfma_f32_16x16x32_bf16 v[0:3], v[186:189], v[232:235], v[0:3]
	s_setprio 0
	s_add_i32 s68, s68, 2
	s_add_u32 s62, s62, 0x100
	s_addc_u32 s63, s63, 0
	s_add_u32 s20, s20, 0x100
	s_addc_u32 s21, s21, 0
	s_cmp_gt_u32 s68, 13

.LBB0_318:
	s_ashr_i32 s15, s14, 31
	s_lshl_b64 s[16:17], s[14:15], 19
	s_add_u32 s16, s37, s16
	s_addc_u32 s17, s42, s17
	s_and_b64 s[18:19], s[6:7], exec
	s_cselect_b32 s9, s17, s25
	s_cselect_b32 s15, s16, s24
	s_ashr_i32 s13, s12, 31
	s_lshl_b64 s[18:19], s[12:13], 19
	s_add_u32 s18, s38, s18
	s_addc_u32 s19, s39, s19
	s_and_b64 s[26:27], s[6:7], exec
	s_cselect_b32 s13, s19, s23
	s_cselect_b32 s21, s18, s22
	s_add_u32 s44, s22, 0x100
	s_addc_u32 s62, s23, 0
	s_add_u32 s22, s24, 0x40080
	s_addc_u32 s23, s25, 0
	s_mov_b32 s63, -2
	s_add_u32 s24, s22, 0xfffc0080
	s_addc_u32 s25, s23, -1
	s_add_i32 s64, 0, 0x10000
	s_cmp_eq_u32 s63, 12
	s_cselect_b32 s27, s9, s25
	s_cselect_b32 s26, s15, s24
	s_cselect_b32 s25, s13, s62
	s_cselect_b32 s24, s21, s44
	s_add_i32 s68, 0, 0x14000
	v_add_u32_e32 v112, s64, v159
	v_add_u32_e32 v165, s68, v159
	ds_read_b128 v[96:99], v112
	ds_read_b128 v[100:103], v112 offset:1024
	ds_read_b128 v[108:111], v112 offset:2048
	ds_read_b128 v[112:115], v112 offset:3072
	ds_read_b128 v[154:157], v165
	ds_read_b128 v[166:169], v165 offset:1024
	ds_read_b128 v[170:173], v165 offset:2048
	ds_read_b128 v[182:185], v165 offset:3072
	v_lshl_add_u64 v[220:221], s[22:23], 0, v[152:153]
	s_add_i32 m0, s50, 0xc000
	ds_read_b128 v[186:189], v164
	ds_read_b128 v[190:193], v164 offset:1024
	ds_read_b128 v[194:197], v164 offset:2048
	ds_read_b128 v[198:201], v164 offset:3072
	ds_read_b128 v[202:205], v164 offset:4096
	ds_read_b128 v[206:209], v164 offset:5120
	ds_read_b128 v[210:213], v164 offset:6144
	ds_read_b128 v[228:231], v164 offset:7168
	global_load_lds_dwordx4 v[220:221], off
	v_lshl_add_u64 v[220:221], s[22:23], 0, v[150:151]
	s_add_i32 m0, s50, 0xe000
	s_nop 0
	global_load_lds_dwordx4 v[220:221], off
	s_waitcnt vmcnt(8)
	s_waitcnt lgkmcnt(0)
	s_barrier
	s_setprio 1
	v_mfma_f32_16x16x32_bf16 v[140:143], v[96:99], v[186:189], 0
	v_mfma_f32_16x16x32_bf16 v[136:139], v[108:111], v[186:189], 0
	v_mfma_f32_16x16x32_bf16 v[124:127], v[96:99], v[194:197], 0
	v_mfma_f32_16x16x32_bf16 v[120:123], v[108:111], v[194:197], 0
	v_mfma_f32_16x16x32_bf16 v[92:95], v[96:99], v[202:205], 0
	v_mfma_f32_16x16x32_bf16 v[88:91], v[108:111], v[202:205], 0
	v_mfma_f32_16x16x32_bf16 v[76:79], v[96:99], v[210:213], 0
	v_mfma_f32_16x16x32_bf16 v[72:75], v[108:111], v[210:213], 0
	v_mfma_f32_16x16x32_bf16 v[140:143], v[100:103], v[190:193], v[140:143]
	v_mfma_f32_16x16x32_bf16 v[136:139], v[112:115], v[190:193], v[136:139]
	v_mfma_f32_16x16x32_bf16 v[124:127], v[100:103], v[198:201], v[124:127]
	v_mfma_f32_16x16x32_bf16 v[120:123], v[112:115], v[198:201], v[120:123]
	v_mfma_f32_16x16x32_bf16 v[92:95], v[100:103], v[206:209], v[92:95]
	v_mfma_f32_16x16x32_bf16 v[88:91], v[112:115], v[206:209], v[88:91]
	v_mfma_f32_16x16x32_bf16 v[76:79], v[100:103], v[228:231], v[76:79]
	v_mfma_f32_16x16x32_bf16 v[72:75], v[112:115], v[228:231], v[72:75]
	v_mfma_f32_16x16x32_bf16 v[132:135], v[154:157], v[186:189], 0
	v_mfma_f32_16x16x32_bf16 v[128:131], v[170:173], v[186:189], 0
	v_mfma_f32_16x16x32_bf16 v[116:119], v[154:157], v[194:197], 0
	v_mfma_f32_16x16x32_bf16 v[104:107], v[170:173], v[194:197], 0
	v_mfma_f32_16x16x32_bf16 v[84:87], v[154:157], v[202:205], 0
	v_mfma_f32_16x16x32_bf16 v[80:83], v[170:173], v[202:205], 0
	v_mfma_f32_16x16x32_bf16 v[68:71], v[154:157], v[210:213], 0
	v_mfma_f32_16x16x32_bf16 v[64:67], v[170:173], v[210:213], 0
	v_mfma_f32_16x16x32_bf16 v[132:135], v[166:169], v[190:193], v[132:135]
	v_mfma_f32_16x16x32_bf16 v[128:131], v[182:185], v[190:193], v[128:131]
	v_mfma_f32_16x16x32_bf16 v[116:119], v[166:169], v[198:201], v[116:119]
	v_mfma_f32_16x16x32_bf16 v[104:107], v[182:185], v[198:201], v[104:107]
	s_setprio 2
	s_barrier
	v_mfma_f32_16x16x32_bf16 v[84:87], v[166:169], v[206:209], v[84:87]
	v_mfma_f32_16x16x32_bf16 v[80:83], v[182:185], v[206:209], v[80:83]
	v_mfma_f32_16x16x32_bf16 v[68:71], v[166:169], v[228:231], v[68:71]
	v_mfma_f32_16x16x32_bf16 v[64:67], v[182:185], v[228:231], v[64:67]
	s_setprio 0
	s_add_i32 s64, s64, s43
	v_lshl_add_u64 v[220:221], s[24:25], 0, v[176:177]
	s_mov_b32 m0, s64
	ds_read_b128 v[186:189], v164 offset:16384
	ds_read_b128 v[190:193], v164 offset:17408
	ds_read_b128 v[194:197], v164 offset:18432
	ds_read_b128 v[198:201], v164 offset:19456
	ds_read_b128 v[202:205], v164 offset:20480
	ds_read_b128 v[206:209], v164 offset:21504
	ds_read_b128 v[210:213], v164 offset:22528
	ds_read_b128 v[228:231], v164 offset:23552
	global_load_lds_dwordx4 v[220:221], off
	s_add_i32 m0, s64, 0x2000
	s_add_u32 s64, s24, 0x40000
	v_lshl_add_u64 v[222:223], s[24:25], 0, v[148:149]
	s_addc_u32 s65, s25, 0
	s_add_i32 s68, s68, s43
	global_load_lds_dwordx4 v[222:223], off
	v_lshl_add_u64 v[226:227], s[64:65], 0, v[176:177]
	s_mov_b32 m0, s68
	v_lshl_add_u64 v[232:233], s[26:27], 0, v[146:147]
	global_load_lds_dwordx4 v[226:227], off
	v_lshl_add_u64 v[226:227], s[64:65], 0, v[148:149]
	s_add_i32 m0, s68, 0x2000
	s_nop 0
	global_load_lds_dwordx4 v[226:227], off
	v_lshl_add_u64 v[226:227], s[26:27], 0, v[144:145]
	s_mov_b32 m0, s50
	s_nop 0
	global_load_lds_dwordx4 v[226:227], off
	s_mov_b32 m0, s51
	s_nop 0
	global_load_lds_dwordx4 v[232:233], off
	s_waitcnt vmcnt(8)
	s_waitcnt lgkmcnt(0)
	s_barrier
	s_setprio 1
	v_mfma_f32_16x16x32_bf16 v[60:63], v[96:99], v[186:189], 0
	v_mfma_f32_16x16x32_bf16 v[56:59], v[108:111], v[186:189], 0
	v_mfma_f32_16x16x32_bf16 v[44:47], v[96:99], v[194:197], 0
	v_mfma_f32_16x16x32_bf16 v[40:43], v[108:111], v[194:197], 0
	v_mfma_f32_16x16x32_bf16 v[28:31], v[96:99], v[202:205], 0
	v_mfma_f32_16x16x32_bf16 v[24:27], v[108:111], v[202:205], 0
	v_mfma_f32_16x16x32_bf16 v[12:15], v[96:99], v[210:213], 0
	v_mfma_f32_16x16x32_bf16 v[8:11], v[108:111], v[210:213], 0
	v_mfma_f32_16x16x32_bf16 v[60:63], v[100:103], v[190:193], v[60:63]
	v_mfma_f32_16x16x32_bf16 v[56:59], v[112:115], v[190:193], v[56:59]
	v_mfma_f32_16x16x32_bf16 v[44:47], v[100:103], v[198:201], v[44:47]
	v_mfma_f32_16x16x32_bf16 v[40:43], v[112:115], v[198:201], v[40:43]
	v_mfma_f32_16x16x32_bf16 v[28:31], v[100:103], v[206:209], v[28:31]
	v_mfma_f32_16x16x32_bf16 v[24:27], v[112:115], v[206:209], v[24:27]
	v_mfma_f32_16x16x32_bf16 v[12:15], v[100:103], v[228:231], v[12:15]
	v_mfma_f32_16x16x32_bf16 v[8:11], v[112:115], v[228:231], v[8:11]
	v_mfma_f32_16x16x32_bf16 v[52:55], v[154:157], v[186:189], 0
	v_mfma_f32_16x16x32_bf16 v[48:51], v[170:173], v[186:189], 0
	v_mfma_f32_16x16x32_bf16 v[36:39], v[154:157], v[194:197], 0
	v_mfma_f32_16x16x32_bf16 v[32:35], v[170:173], v[194:197], 0
	v_mfma_f32_16x16x32_bf16 v[20:23], v[154:157], v[202:205], 0
	v_mfma_f32_16x16x32_bf16 v[16:19], v[170:173], v[202:205], 0
	v_mfma_f32_16x16x32_bf16 v[4:7], v[154:157], v[210:213], 0
	v_mfma_f32_16x16x32_bf16 v[0:3], v[170:173], v[210:213], 0
	v_mfma_f32_16x16x32_bf16 v[52:55], v[166:169], v[190:193], v[52:55]
	v_mfma_f32_16x16x32_bf16 v[48:51], v[182:185], v[190:193], v[48:51]
	v_mfma_f32_16x16x32_bf16 v[36:39], v[166:169], v[198:201], v[36:39]
	v_mfma_f32_16x16x32_bf16 v[32:35], v[182:185], v[198:201], v[32:35]
	s_setprio 2
	s_barrier
	v_mfma_f32_16x16x32_bf16 v[20:23], v[166:169], v[206:209], v[20:23]
	v_mfma_f32_16x16x32_bf16 v[16:19], v[182:185], v[206:209], v[16:19]
	v_mfma_f32_16x16x32_bf16 v[4:7], v[166:169], v[228:231], v[4:7]
	v_mfma_f32_16x16x32_bf16 v[0:3], v[182:185], v[228:231], v[0:3]
	s_setprio 0
	s_add_i32 s64, 0, 0x18000
	s_add_i32 s65, 0, 0x1c000
	v_add_u32_e32 v112, s64, v159
	v_add_u32_e32 v165, s65, v159
	ds_read_b128 v[96:99], v112
	ds_read_b128 v[100:103], v112 offset:1024
	ds_read_b128 v[108:111], v112 offset:2048
	ds_read_b128 v[112:115], v112 offset:3072
	ds_read_b128 v[154:157], v165
	ds_read_b128 v[166:169], v165 offset:1024
	ds_read_b128 v[170:173], v165 offset:2048
	ds_read_b128 v[182:185], v165 offset:3072
	s_add_u32 s26, s26, 0x40000
	s_addc_u32 s27, s27, 0
	s_mov_b32 m0, s52
	v_lshl_add_u64 v[234:235], s[26:27], 0, v[144:145]
	ds_read_b128 v[186:189], v164 offset:32768
	ds_read_b128 v[190:193], v164 offset:33792
	ds_read_b128 v[194:197], v164 offset:34816
	ds_read_b128 v[198:201], v164 offset:35840
	ds_read_b128 v[202:205], v164 offset:36864
	ds_read_b128 v[206:209], v164 offset:37888
	ds_read_b128 v[210:213], v164 offset:38912
	ds_read_b128 v[228:231], v164 offset:39936
	global_load_lds_dwordx4 v[234:235], off
	v_lshl_add_u64 v[234:235], s[26:27], 0, v[146:147]
	s_mov_b32 m0, s53
	s_nop 0
	global_load_lds_dwordx4 v[234:235], off
	s_waitcnt vmcnt(8)
	s_waitcnt lgkmcnt(0)
	s_barrier
	s_setprio 1
	v_mfma_f32_16x16x32_bf16 v[140:143], v[96:99], v[186:189], v[140:143]
	v_mfma_f32_16x16x32_bf16 v[136:139], v[108:111], v[186:189], v[136:139]
	v_mfma_f32_16x16x32_bf16 v[124:127], v[96:99], v[194:197], v[124:127]
	v_mfma_f32_16x16x32_bf16 v[120:123], v[108:111], v[194:197], v[120:123]
	v_mfma_f32_16x16x32_bf16 v[92:95], v[96:99], v[202:205], v[92:95]
	v_mfma_f32_16x16x32_bf16 v[88:91], v[108:111], v[202:205], v[88:91]
	v_mfma_f32_16x16x32_bf16 v[76:79], v[96:99], v[210:213], v[76:79]
	v_mfma_f32_16x16x32_bf16 v[72:75], v[108:111], v[210:213], v[72:75]
	v_mfma_f32_16x16x32_bf16 v[140:143], v[100:103], v[190:193], v[140:143]
	v_mfma_f32_16x16x32_bf16 v[136:139], v[112:115], v[190:193], v[136:139]
	v_mfma_f32_16x16x32_bf16 v[124:127], v[100:103], v[198:201], v[124:127]
	v_mfma_f32_16x16x32_bf16 v[120:123], v[112:115], v[198:201], v[120:123]
	v_mfma_f32_16x16x32_bf16 v[92:95], v[100:103], v[206:209], v[92:95]
	v_mfma_f32_16x16x32_bf16 v[88:91], v[112:115], v[206:209], v[88:91]
	v_mfma_f32_16x16x32_bf16 v[76:79], v[100:103], v[228:231], v[76:79]
	v_mfma_f32_16x16x32_bf16 v[72:75], v[112:115], v[228:231], v[72:75]
	v_mfma_f32_16x16x32_bf16 v[132:135], v[154:157], v[186:189], v[132:135]
	v_mfma_f32_16x16x32_bf16 v[128:131], v[170:173], v[186:189], v[128:131]
	v_mfma_f32_16x16x32_bf16 v[116:119], v[154:157], v[194:197], v[116:119]
	v_mfma_f32_16x16x32_bf16 v[104:107], v[170:173], v[194:197], v[104:107]
	v_mfma_f32_16x16x32_bf16 v[84:87], v[154:157], v[202:205], v[84:87]
	v_mfma_f32_16x16x32_bf16 v[80:83], v[170:173], v[202:205], v[80:83]
	v_mfma_f32_16x16x32_bf16 v[68:71], v[154:157], v[210:213], v[68:71]
	v_mfma_f32_16x16x32_bf16 v[64:67], v[170:173], v[210:213], v[64:67]
	v_mfma_f32_16x16x32_bf16 v[132:135], v[166:169], v[190:193], v[132:135]
	v_mfma_f32_16x16x32_bf16 v[128:131], v[182:185], v[190:193], v[128:131]
	v_mfma_f32_16x16x32_bf16 v[116:119], v[166:169], v[198:201], v[116:119]
	v_mfma_f32_16x16x32_bf16 v[104:107], v[182:185], v[198:201], v[104:107]
	s_setprio 2
	s_barrier
	v_mfma_f32_16x16x32_bf16 v[84:87], v[166:169], v[206:209], v[84:87]
	v_mfma_f32_16x16x32_bf16 v[80:83], v[182:185], v[206:209], v[80:83]
	v_mfma_f32_16x16x32_bf16 v[68:71], v[166:169], v[228:231], v[68:71]
	v_mfma_f32_16x16x32_bf16 v[64:67], v[182:185], v[228:231], v[64:67]
	s_setprio 0
	s_add_i32 s26, s64, s43
	v_lshl_add_u64 v[220:221], v[220:221], 0, s[34:35]
	s_mov_b32 m0, s26
	ds_read_b128 v[186:189], v164 offset:49152
	ds_read_b128 v[190:193], v164 offset:50176
	ds_read_b128 v[194:197], v164 offset:51200
	ds_read_b128 v[198:201], v164 offset:52224
	ds_read_b128 v[202:205], v164 offset:53248
	ds_read_b128 v[206:209], v164 offset:54272
	ds_read_b128 v[210:213], v164 offset:55296
	ds_read_b128 v[228:231], v164 offset:56320
	global_load_lds_dwordx4 v[220:221], off
	s_add_i32 m0, s26, 0x2000
	s_add_u32 s24, s24, 0x40080
	v_lshl_add_u64 v[220:221], v[222:223], 0, s[34:35]
	s_addc_u32 s25, s25, 0
	s_add_i32 s26, s65, s43
	global_load_lds_dwordx4 v[220:221], off
	v_lshl_add_u64 v[220:221], s[24:25], 0, v[176:177]
	s_mov_b32 m0, s26
	s_nop 0
	global_load_lds_dwordx4 v[220:221], off
	v_lshl_add_u64 v[220:221], s[24:25], 0, v[148:149]
	s_add_i32 m0, s26, 0x2000
	s_nop 0
	global_load_lds_dwordx4 v[220:221], off
	v_lshl_add_u64 v[220:221], v[226:227], 0, s[34:35]
	s_mov_b32 m0, s57
	s_nop 0
	global_load_lds_dwordx4 v[220:221], off
	v_lshl_add_u64 v[220:221], v[232:233], 0, s[34:35]
	s_mov_b32 m0, s58
	s_nop 0
	global_load_lds_dwordx4 v[220:221], off
	s_waitcnt vmcnt(8)
	s_waitcnt lgkmcnt(0)
	s_barrier
	s_setprio 1
	v_mfma_f32_16x16x32_bf16 v[60:63], v[96:99], v[186:189], v[60:63]
	v_mfma_f32_16x16x32_bf16 v[56:59], v[108:111], v[186:189], v[56:59]
	v_mfma_f32_16x16x32_bf16 v[44:47], v[96:99], v[194:197], v[44:47]
	v_mfma_f32_16x16x32_bf16 v[40:43], v[108:111], v[194:197], v[40:43]
	v_mfma_f32_16x16x32_bf16 v[28:31], v[96:99], v[202:205], v[28:31]
	v_mfma_f32_16x16x32_bf16 v[24:27], v[108:111], v[202:205], v[24:27]
	v_mfma_f32_16x16x32_bf16 v[12:15], v[96:99], v[210:213], v[12:15]
	v_mfma_f32_16x16x32_bf16 v[8:11], v[108:111], v[210:213], v[8:11]
	v_mfma_f32_16x16x32_bf16 v[60:63], v[100:103], v[190:193], v[60:63]
	v_mfma_f32_16x16x32_bf16 v[56:59], v[112:115], v[190:193], v[56:59]
	v_mfma_f32_16x16x32_bf16 v[44:47], v[100:103], v[198:201], v[44:47]
	v_mfma_f32_16x16x32_bf16 v[40:43], v[112:115], v[198:201], v[40:43]
	v_mfma_f32_16x16x32_bf16 v[28:31], v[100:103], v[206:209], v[28:31]
	v_mfma_f32_16x16x32_bf16 v[24:27], v[112:115], v[206:209], v[24:27]
	v_mfma_f32_16x16x32_bf16 v[12:15], v[100:103], v[228:231], v[12:15]
	v_mfma_f32_16x16x32_bf16 v[8:11], v[112:115], v[228:231], v[8:11]
	v_mfma_f32_16x16x32_bf16 v[52:55], v[154:157], v[186:189], v[52:55]
	v_mfma_f32_16x16x32_bf16 v[48:51], v[170:173], v[186:189], v[48:51]
	v_mfma_f32_16x16x32_bf16 v[36:39], v[154:157], v[194:197], v[36:39]
	v_mfma_f32_16x16x32_bf16 v[32:35], v[170:173], v[194:197], v[32:35]
	v_mfma_f32_16x16x32_bf16 v[20:23], v[154:157], v[202:205], v[20:23]
	v_mfma_f32_16x16x32_bf16 v[16:19], v[170:173], v[202:205], v[16:19]
	v_mfma_f32_16x16x32_bf16 v[4:7], v[154:157], v[210:213], v[4:7]
	v_mfma_f32_16x16x32_bf16 v[0:3], v[170:173], v[210:213], v[0:3]
	v_mfma_f32_16x16x32_bf16 v[52:55], v[166:169], v[190:193], v[52:55]
	v_mfma_f32_16x16x32_bf16 v[48:51], v[182:185], v[190:193], v[48:51]
	v_mfma_f32_16x16x32_bf16 v[36:39], v[166:169], v[198:201], v[36:39]
	v_mfma_f32_16x16x32_bf16 v[32:35], v[182:185], v[198:201], v[32:35]
	s_setprio 2
	s_barrier
	v_mfma_f32_16x16x32_bf16 v[20:23], v[166:169], v[206:209], v[20:23]
	v_mfma_f32_16x16x32_bf16 v[16:19], v[182:185], v[206:209], v[16:19]
	v_mfma_f32_16x16x32_bf16 v[4:7], v[166:169], v[228:231], v[4:7]
	v_mfma_f32_16x16x32_bf16 v[0:3], v[182:185], v[228:231], v[0:3]
	s_setprio 0
	s_add_i32 s63, s63, 2
	s_add_u32 s44, s44, 0x100
	s_addc_u32 s62, s62, 0
	s_add_u32 s22, s22, 0x100
	s_addc_u32 s23, s23, 0
	s_cmp_gt_u32 s63, 13
	s_cbranch_scc1 .Lpeel_exit_0

.Lpeel_exit_0:
	s_and_b64 vcc, exec, s[10:11]
	s_cbranch_vccz .LBB0_322
	s_barrier

.LBB0_633:
	s_ashr_i32 s13, s12, 31
	s_lshl_b64 s[14:15], s[12:13], 19
	s_add_u32 s14, s37, s14
	s_addc_u32 s15, s42, s15
	s_and_b64 s[16:17], s[4:5], exec
	s_cselect_b32 s13, s15, s23
	s_cselect_b32 s19, s14, s22
	s_ashr_i32 s11, s10, 31
	s_lshl_b64 s[16:17], s[10:11], 19
	s_add_u32 s16, s29, s16
	s_addc_u32 s17, s43, s17
	s_and_b64 s[24:25], s[4:5], exec
	s_cselect_b32 s11, s17, s21
	s_cselect_b32 s60, s16, s20
	s_add_u32 s61, s20, 0x100
	s_addc_u32 s62, s21, 0
	s_add_u32 s20, s22, 0x40080
	s_addc_u32 s21, s23, 0
	s_mov_b32 s63, -2
	s_add_u32 s22, s20, 0xfffc0080
	s_addc_u32 s23, s21, -1
	s_add_i32 s64, 0, 0x10000
	s_cmp_eq_u32 s63, 12
	s_cselect_b32 s25, s13, s23
	s_cselect_b32 s24, s19, s22
	s_cselect_b32 s23, s11, s62
	s_cselect_b32 s22, s60, s61
	s_add_i32 s68, 0, 0x14000
	s_waitcnt vmcnt(0) lgkmcnt(0)
	v_add_u32_e32 v140, s64, v175
	v_add_u32_e32 v170, s68, v175
	ds_read_b128 v[128:131], v140
	ds_read_b128 v[132:135], v140 offset:1024
	ds_read_b128 v[136:139], v140 offset:2048
	ds_read_b128 v[140:143], v140 offset:3072
	ds_read_b128 v[144:147], v170
	ds_read_b128 v[162:165], v170 offset:1024
	ds_read_b128 v[166:169], v170 offset:2048
	ds_read_b128 v[170:173], v170 offset:3072
	v_lshl_add_u64 v[220:221], s[20:21], 0, v[160:161]
	s_add_i32 m0, s50, 0xc000
	ds_read_b128 v[186:189], v185
	ds_read_b128 v[190:193], v185 offset:1024
	ds_read_b128 v[194:197], v185 offset:2048
	ds_read_b128 v[198:201], v185 offset:3072
	ds_read_b128 v[202:205], v185 offset:4096
	ds_read_b128 v[206:209], v185 offset:5120
	ds_read_b128 v[210:213], v185 offset:6144
	ds_read_b128 v[228:231], v185 offset:7168
	global_load_lds_dwordx4 v[220:221], off
	v_lshl_add_u64 v[220:221], s[20:21], 0, v[158:159]
	s_add_i32 m0, s50, 0xe000
	s_nop 0
	global_load_lds_dwordx4 v[220:221], off
	s_waitcnt vmcnt(8)
	s_waitcnt lgkmcnt(0)
	s_barrier
	s_setprio 1
	v_mfma_f32_16x16x32_bf16 v[124:127], v[128:131], v[186:189], 0
	v_mfma_f32_16x16x32_bf16 v[120:123], v[136:139], v[186:189], 0
	v_mfma_f32_16x16x32_bf16 v[108:111], v[128:131], v[194:197], 0
	v_mfma_f32_16x16x32_bf16 v[104:107], v[136:139], v[194:197], 0
	v_mfma_f32_16x16x32_bf16 v[92:95], v[128:131], v[202:205], 0
	v_mfma_f32_16x16x32_bf16 v[88:91], v[136:139], v[202:205], 0
	v_mfma_f32_16x16x32_bf16 v[76:79], v[128:131], v[210:213], 0
	v_mfma_f32_16x16x32_bf16 v[72:75], v[136:139], v[210:213], 0
	v_mfma_f32_16x16x32_bf16 v[124:127], v[132:135], v[190:193], v[124:127]
	v_mfma_f32_16x16x32_bf16 v[120:123], v[140:143], v[190:193], v[120:123]
	v_mfma_f32_16x16x32_bf16 v[108:111], v[132:135], v[198:201], v[108:111]
	v_mfma_f32_16x16x32_bf16 v[104:107], v[140:143], v[198:201], v[104:107]
	v_mfma_f32_16x16x32_bf16 v[92:95], v[132:135], v[206:209], v[92:95]
	v_mfma_f32_16x16x32_bf16 v[88:91], v[140:143], v[206:209], v[88:91]
	v_mfma_f32_16x16x32_bf16 v[76:79], v[132:135], v[228:231], v[76:79]
	v_mfma_f32_16x16x32_bf16 v[72:75], v[140:143], v[228:231], v[72:75]
	v_mfma_f32_16x16x32_bf16 v[116:119], v[144:147], v[186:189], 0
	v_mfma_f32_16x16x32_bf16 v[112:115], v[166:169], v[186:189], 0
	v_mfma_f32_16x16x32_bf16 v[100:103], v[144:147], v[194:197], 0
	v_mfma_f32_16x16x32_bf16 v[96:99], v[166:169], v[194:197], 0
	v_mfma_f32_16x16x32_bf16 v[84:87], v[144:147], v[202:205], 0
	v_mfma_f32_16x16x32_bf16 v[80:83], v[166:169], v[202:205], 0
	v_mfma_f32_16x16x32_bf16 v[68:71], v[144:147], v[210:213], 0
	v_mfma_f32_16x16x32_bf16 v[64:67], v[166:169], v[210:213], 0
	v_mfma_f32_16x16x32_bf16 v[116:119], v[162:165], v[190:193], v[116:119]
	v_mfma_f32_16x16x32_bf16 v[112:115], v[170:173], v[190:193], v[112:115]
	v_mfma_f32_16x16x32_bf16 v[100:103], v[162:165], v[198:201], v[100:103]
	v_mfma_f32_16x16x32_bf16 v[96:99], v[170:173], v[198:201], v[96:99]
	s_setprio 2
	s_barrier
	v_mfma_f32_16x16x32_bf16 v[84:87], v[162:165], v[206:209], v[84:87]
	v_mfma_f32_16x16x32_bf16 v[80:83], v[170:173], v[206:209], v[80:83]
	v_mfma_f32_16x16x32_bf16 v[68:71], v[162:165], v[228:231], v[68:71]
	v_mfma_f32_16x16x32_bf16 v[64:67], v[170:173], v[228:231], v[64:67]
	s_setprio 0
	s_add_i32 s64, s64, s46
	v_lshl_add_u64 v[220:221], s[22:23], 0, v[152:153]
	s_mov_b32 m0, s64
	ds_read_b128 v[186:189], v185 offset:16384
	ds_read_b128 v[190:193], v185 offset:17408
	ds_read_b128 v[194:197], v185 offset:18432
	ds_read_b128 v[198:201], v185 offset:19456
	ds_read_b128 v[202:205], v185 offset:20480
	ds_read_b128 v[206:209], v185 offset:21504
	ds_read_b128 v[210:213], v185 offset:22528
	ds_read_b128 v[228:231], v185 offset:23552
	global_load_lds_dwordx4 v[220:221], off
	s_add_i32 m0, s64, 0x2000
	s_add_u32 s64, s22, 0x40000
	v_lshl_add_u64 v[222:223], s[22:23], 0, v[148:149]
	s_addc_u32 s65, s23, 0
	s_add_i32 s68, s68, s46
	global_load_lds_dwordx4 v[222:223], off
	v_lshl_add_u64 v[226:227], s[64:65], 0, v[152:153]
	s_mov_b32 m0, s68
	v_lshl_add_u64 v[232:233], s[24:25], 0, v[150:151]
	global_load_lds_dwordx4 v[226:227], off
	v_lshl_add_u64 v[226:227], s[64:65], 0, v[148:149]
	s_add_i32 m0, s68, 0x2000
	s_nop 0
	global_load_lds_dwordx4 v[226:227], off
	v_lshl_add_u64 v[226:227], s[24:25], 0, v[154:155]
	s_mov_b32 m0, s50
	s_nop 0
	global_load_lds_dwordx4 v[226:227], off
	s_mov_b32 m0, s51
	s_nop 0
	global_load_lds_dwordx4 v[232:233], off
	s_waitcnt vmcnt(8)
	s_waitcnt lgkmcnt(0)
	s_barrier
	s_setprio 1
	v_mfma_f32_16x16x32_bf16 v[60:63], v[128:131], v[186:189], 0
	v_mfma_f32_16x16x32_bf16 v[56:59], v[136:139], v[186:189], 0
	v_mfma_f32_16x16x32_bf16 v[48:51], v[128:131], v[194:197], 0
	v_mfma_f32_16x16x32_bf16 v[40:43], v[136:139], v[194:197], 0
	v_mfma_f32_16x16x32_bf16 v[32:35], v[128:131], v[202:205], 0
	v_mfma_f32_16x16x32_bf16 v[24:27], v[136:139], v[202:205], 0
	v_mfma_f32_16x16x32_bf16 v[16:19], v[128:131], v[210:213], 0
	v_mfma_f32_16x16x32_bf16 v[8:11], v[136:139], v[210:213], 0
	v_mfma_f32_16x16x32_bf16 v[60:63], v[132:135], v[190:193], v[60:63]
	v_mfma_f32_16x16x32_bf16 v[56:59], v[140:143], v[190:193], v[56:59]
	v_mfma_f32_16x16x32_bf16 v[48:51], v[132:135], v[198:201], v[48:51]
	v_mfma_f32_16x16x32_bf16 v[40:43], v[140:143], v[198:201], v[40:43]
	v_mfma_f32_16x16x32_bf16 v[32:35], v[132:135], v[206:209], v[32:35]
	v_mfma_f32_16x16x32_bf16 v[24:27], v[140:143], v[206:209], v[24:27]
	v_mfma_f32_16x16x32_bf16 v[16:19], v[132:135], v[228:231], v[16:19]
	v_mfma_f32_16x16x32_bf16 v[8:11], v[140:143], v[228:231], v[8:11]
	v_mfma_f32_16x16x32_bf16 v[52:55], v[144:147], v[186:189], 0
	v_mfma_f32_16x16x32_bf16 v[44:47], v[166:169], v[186:189], 0
	v_mfma_f32_16x16x32_bf16 v[36:39], v[144:147], v[194:197], 0
	v_mfma_f32_16x16x32_bf16 v[28:31], v[166:169], v[194:197], 0
	v_mfma_f32_16x16x32_bf16 v[20:23], v[144:147], v[202:205], 0
	v_mfma_f32_16x16x32_bf16 v[12:15], v[166:169], v[202:205], 0
	v_mfma_f32_16x16x32_bf16 v[4:7], v[144:147], v[210:213], 0
	v_mfma_f32_16x16x32_bf16 v[0:3], v[166:169], v[210:213], 0
	v_mfma_f32_16x16x32_bf16 v[52:55], v[162:165], v[190:193], v[52:55]
	v_mfma_f32_16x16x32_bf16 v[44:47], v[170:173], v[190:193], v[44:47]
	v_mfma_f32_16x16x32_bf16 v[36:39], v[162:165], v[198:201], v[36:39]
	v_mfma_f32_16x16x32_bf16 v[28:31], v[170:173], v[198:201], v[28:31]
	s_setprio 2
	s_barrier
	v_mfma_f32_16x16x32_bf16 v[20:23], v[162:165], v[206:209], v[20:23]
	v_mfma_f32_16x16x32_bf16 v[12:15], v[170:173], v[206:209], v[12:15]
	v_mfma_f32_16x16x32_bf16 v[4:7], v[162:165], v[228:231], v[4:7]
	v_mfma_f32_16x16x32_bf16 v[0:3], v[170:173], v[228:231], v[0:3]
	s_setprio 0
	s_add_i32 s64, 0, 0x18000
	s_add_i32 s65, 0, 0x1c000
	v_add_u32_e32 v140, s64, v175
	v_add_u32_e32 v170, s65, v175
	ds_read_b128 v[128:131], v140
	ds_read_b128 v[132:135], v140 offset:1024
	ds_read_b128 v[136:139], v140 offset:2048
	ds_read_b128 v[140:143], v140 offset:3072
	ds_read_b128 v[144:147], v170
	ds_read_b128 v[162:165], v170 offset:1024
	ds_read_b128 v[166:169], v170 offset:2048
	ds_read_b128 v[170:173], v170 offset:3072
	s_add_u32 s24, s24, 0x40000
	s_addc_u32 s25, s25, 0
	s_mov_b32 m0, s52
	v_lshl_add_u64 v[234:235], s[24:25], 0, v[154:155]
	ds_read_b128 v[186:189], v185 offset:32768
	ds_read_b128 v[190:193], v185 offset:33792
	ds_read_b128 v[194:197], v185 offset:34816
	ds_read_b128 v[198:201], v185 offset:35840
	ds_read_b128 v[202:205], v185 offset:36864
	ds_read_b128 v[206:209], v185 offset:37888
	ds_read_b128 v[210:213], v185 offset:38912
	ds_read_b128 v[228:231], v185 offset:39936
	global_load_lds_dwordx4 v[234:235], off
	v_lshl_add_u64 v[234:235], s[24:25], 0, v[150:151]
	s_mov_b32 m0, s53
	s_nop 0
	global_load_lds_dwordx4 v[234:235], off
	s_waitcnt vmcnt(8)
	s_waitcnt lgkmcnt(0)
	s_barrier
	s_setprio 1
	v_mfma_f32_16x16x32_bf16 v[124:127], v[128:131], v[186:189], v[124:127]
	v_mfma_f32_16x16x32_bf16 v[120:123], v[136:139], v[186:189], v[120:123]
	v_mfma_f32_16x16x32_bf16 v[108:111], v[128:131], v[194:197], v[108:111]
	v_mfma_f32_16x16x32_bf16 v[104:107], v[136:139], v[194:197], v[104:107]
	v_mfma_f32_16x16x32_bf16 v[92:95], v[128:131], v[202:205], v[92:95]
	v_mfma_f32_16x16x32_bf16 v[88:91], v[136:139], v[202:205], v[88:91]
	v_mfma_f32_16x16x32_bf16 v[76:79], v[128:131], v[210:213], v[76:79]
	v_mfma_f32_16x16x32_bf16 v[72:75], v[136:139], v[210:213], v[72:75]
	v_mfma_f32_16x16x32_bf16 v[124:127], v[132:135], v[190:193], v[124:127]
	v_mfma_f32_16x16x32_bf16 v[120:123], v[140:143], v[190:193], v[120:123]
	v_mfma_f32_16x16x32_bf16 v[108:111], v[132:135], v[198:201], v[108:111]
	v_mfma_f32_16x16x32_bf16 v[104:107], v[140:143], v[198:201], v[104:107]
	v_mfma_f32_16x16x32_bf16 v[92:95], v[132:135], v[206:209], v[92:95]
	v_mfma_f32_16x16x32_bf16 v[88:91], v[140:143], v[206:209], v[88:91]
	v_mfma_f32_16x16x32_bf16 v[76:79], v[132:135], v[228:231], v[76:79]
	v_mfma_f32_16x16x32_bf16 v[72:75], v[140:143], v[228:231], v[72:75]
	v_mfma_f32_16x16x32_bf16 v[116:119], v[144:147], v[186:189], v[116:119]
	v_mfma_f32_16x16x32_bf16 v[112:115], v[166:169], v[186:189], v[112:115]
	v_mfma_f32_16x16x32_bf16 v[100:103], v[144:147], v[194:197], v[100:103]
	v_mfma_f32_16x16x32_bf16 v[96:99], v[166:169], v[194:197], v[96:99]
	v_mfma_f32_16x16x32_bf16 v[84:87], v[144:147], v[202:205], v[84:87]
	v_mfma_f32_16x16x32_bf16 v[80:83], v[166:169], v[202:205], v[80:83]
	v_mfma_f32_16x16x32_bf16 v[68:71], v[144:147], v[210:213], v[68:71]
	v_mfma_f32_16x16x32_bf16 v[64:67], v[166:169], v[210:213], v[64:67]
	v_mfma_f32_16x16x32_bf16 v[116:119], v[162:165], v[190:193], v[116:119]
	v_mfma_f32_16x16x32_bf16 v[112:115], v[170:173], v[190:193], v[112:115]
	v_mfma_f32_16x16x32_bf16 v[100:103], v[162:165], v[198:201], v[100:103]
	v_mfma_f32_16x16x32_bf16 v[96:99], v[170:173], v[198:201], v[96:99]
	s_setprio 2
	s_barrier
	v_mfma_f32_16x16x32_bf16 v[84:87], v[162:165], v[206:209], v[84:87]
	v_mfma_f32_16x16x32_bf16 v[80:83], v[170:173], v[206:209], v[80:83]
	v_mfma_f32_16x16x32_bf16 v[68:71], v[162:165], v[228:231], v[68:71]
	v_mfma_f32_16x16x32_bf16 v[64:67], v[170:173], v[228:231], v[64:67]
	s_setprio 0
	s_add_i32 s24, s64, s46
	v_lshl_add_u64 v[220:221], v[220:221], 0, s[34:35]
	s_mov_b32 m0, s24
	ds_read_b128 v[186:189], v185 offset:49152
	ds_read_b128 v[190:193], v185 offset:50176
	ds_read_b128 v[194:197], v185 offset:51200
	ds_read_b128 v[198:201], v185 offset:52224
	ds_read_b128 v[202:205], v185 offset:53248
	ds_read_b128 v[206:209], v185 offset:54272
	ds_read_b128 v[210:213], v185 offset:55296
	ds_read_b128 v[228:231], v185 offset:56320
	global_load_lds_dwordx4 v[220:221], off
	s_add_i32 m0, s24, 0x2000
	s_add_u32 s22, s22, 0x40080
	v_lshl_add_u64 v[220:221], v[222:223], 0, s[34:35]
	s_addc_u32 s23, s23, 0
	s_add_i32 s24, s65, s46
	global_load_lds_dwordx4 v[220:221], off
	v_lshl_add_u64 v[220:221], s[22:23], 0, v[152:153]
	s_mov_b32 m0, s24
	s_nop 0
	global_load_lds_dwordx4 v[220:221], off
	v_lshl_add_u64 v[220:221], s[22:23], 0, v[148:149]
	s_add_i32 m0, s24, 0x2000
	s_nop 0
	global_load_lds_dwordx4 v[220:221], off
	v_lshl_add_u64 v[220:221], v[226:227], 0, s[34:35]
	s_mov_b32 m0, s56
	s_nop 0
	global_load_lds_dwordx4 v[220:221], off
	v_lshl_add_u64 v[220:221], v[232:233], 0, s[34:35]
	s_mov_b32 m0, s57
	s_nop 0
	global_load_lds_dwordx4 v[220:221], off
	s_waitcnt vmcnt(8)
	s_waitcnt lgkmcnt(0)
	s_barrier
	s_setprio 1
	v_mfma_f32_16x16x32_bf16 v[60:63], v[128:131], v[186:189], v[60:63]
	v_mfma_f32_16x16x32_bf16 v[56:59], v[136:139], v[186:189], v[56:59]
	v_mfma_f32_16x16x32_bf16 v[48:51], v[128:131], v[194:197], v[48:51]
	v_mfma_f32_16x16x32_bf16 v[40:43], v[136:139], v[194:197], v[40:43]
	v_mfma_f32_16x16x32_bf16 v[32:35], v[128:131], v[202:205], v[32:35]
	v_mfma_f32_16x16x32_bf16 v[24:27], v[136:139], v[202:205], v[24:27]
	v_mfma_f32_16x16x32_bf16 v[16:19], v[128:131], v[210:213], v[16:19]
	v_mfma_f32_16x16x32_bf16 v[8:11], v[136:139], v[210:213], v[8:11]
	v_mfma_f32_16x16x32_bf16 v[60:63], v[132:135], v[190:193], v[60:63]
	v_mfma_f32_16x16x32_bf16 v[56:59], v[140:143], v[190:193], v[56:59]
	v_mfma_f32_16x16x32_bf16 v[48:51], v[132:135], v[198:201], v[48:51]
	v_mfma_f32_16x16x32_bf16 v[40:43], v[140:143], v[198:201], v[40:43]
	v_mfma_f32_16x16x32_bf16 v[32:35], v[132:135], v[206:209], v[32:35]
	v_mfma_f32_16x16x32_bf16 v[24:27], v[140:143], v[206:209], v[24:27]
	v_mfma_f32_16x16x32_bf16 v[16:19], v[132:135], v[228:231], v[16:19]
	v_mfma_f32_16x16x32_bf16 v[8:11], v[140:143], v[228:231], v[8:11]
	v_mfma_f32_16x16x32_bf16 v[52:55], v[144:147], v[186:189], v[52:55]
	v_mfma_f32_16x16x32_bf16 v[44:47], v[166:169], v[186:189], v[44:47]
	v_mfma_f32_16x16x32_bf16 v[36:39], v[144:147], v[194:197], v[36:39]
	v_mfma_f32_16x16x32_bf16 v[28:31], v[166:169], v[194:197], v[28:31]
	v_mfma_f32_16x16x32_bf16 v[20:23], v[144:147], v[202:205], v[20:23]
	v_mfma_f32_16x16x32_bf16 v[12:15], v[166:169], v[202:205], v[12:15]
	v_mfma_f32_16x16x32_bf16 v[4:7], v[144:147], v[210:213], v[4:7]
	v_mfma_f32_16x16x32_bf16 v[0:3], v[166:169], v[210:213], v[0:3]
	v_mfma_f32_16x16x32_bf16 v[52:55], v[162:165], v[190:193], v[52:55]
	v_mfma_f32_16x16x32_bf16 v[44:47], v[170:173], v[190:193], v[44:47]
	v_mfma_f32_16x16x32_bf16 v[36:39], v[162:165], v[198:201], v[36:39]
	v_mfma_f32_16x16x32_bf16 v[28:31], v[170:173], v[198:201], v[28:31]
	s_setprio 2
	s_barrier
	v_mfma_f32_16x16x32_bf16 v[20:23], v[162:165], v[206:209], v[20:23]
	v_mfma_f32_16x16x32_bf16 v[12:15], v[170:173], v[206:209], v[12:15]
	v_mfma_f32_16x16x32_bf16 v[4:7], v[162:165], v[228:231], v[4:7]
	v_mfma_f32_16x16x32_bf16 v[0:3], v[170:173], v[228:231], v[0:3]
	s_setprio 0
	s_add_i32 s63, s63, 2
	s_add_u32 s61, s61, 0x100
	s_addc_u32 s62, s62, 0
	s_add_u32 s20, s20, 0x100
	s_addc_u32 s21, s21, 0
	s_cmp_gt_u32 s63, 13
	s_cbranch_scc1 .Lpeel_exit_1

.Lpeel_exit_1:
	s_and_b64 vcc, exec, s[8:9]
	s_cbranch_vccz .LBB0_637
	s_barrier

.LBB0_768:
	s_add_u32 s44, s40, 0x100
	s_addc_u32 s55, s41, 0
	s_mov_b32 s92, -2
	s_waitcnt vmcnt(0)
	s_add_u32 s40, s8, 0x100
	s_addc_u32 s41, s9, 0
	s_add_i32 s64, 0, 0x10000
	s_cmp_eq_u32 s92, 40
	s_cselect_b32 s53, s1, s41
	s_cselect_b32 s52, s0, s40
	s_cselect_b32 s51, s39, s55
	s_cselect_b32 s50, s38, s44
	s_add_i32 s65, 0, 0x14000
	v_add_u32_e32 v140, s64, v228
	v_add_u32_e32 v156, s65, v228
	ds_read_b128 v[128:131], v140
	ds_read_b128 v[132:135], v140 offset:1024
	ds_read_b128 v[136:139], v140 offset:2048
	ds_read_b128 v[140:143], v140 offset:3072
	ds_read_b128 v[144:147], v156
	ds_read_b128 v[148:151], v156 offset:1024
	ds_read_b128 v[152:155], v156 offset:2048
	ds_read_b128 v[156:159], v156 offset:3072
	v_lshl_add_u64 v[178:179], s[8:9], 0, v[184:185]
	s_add_i32 m0, s62, 0xc000
	ds_read_b128 v[160:163], v231
	ds_read_b128 v[164:167], v231 offset:1024
	ds_read_b128 v[186:189], v231 offset:2048
	ds_read_b128 v[190:193], v231 offset:3072
	ds_read_b128 v[194:197], v231 offset:4096
	ds_read_b128 v[198:201], v231 offset:5120
	ds_read_b128 v[202:205], v231 offset:6144
	ds_read_b128 v[206:209], v231 offset:7168
	global_load_lds_dwordx4 v[178:179], off
	v_lshl_add_u64 v[178:179], s[8:9], 0, v[182:183]
	s_add_i32 m0, s62, 0xe000
	s_nop 0
	global_load_lds_dwordx4 v[178:179], off
	s_waitcnt vmcnt(8)
	s_waitcnt lgkmcnt(0)
	s_barrier
	s_setprio 1
	v_mfma_f32_16x16x32_bf16 v[124:127], v[128:131], v[160:163], 0
	v_mfma_f32_16x16x32_bf16 v[120:123], v[136:139], v[160:163], 0
	v_mfma_f32_16x16x32_bf16 v[108:111], v[128:131], v[186:189], 0
	v_mfma_f32_16x16x32_bf16 v[104:107], v[136:139], v[186:189], 0
	v_mfma_f32_16x16x32_bf16 v[92:95], v[128:131], v[194:197], 0
	v_mfma_f32_16x16x32_bf16 v[88:91], v[136:139], v[194:197], 0
	v_mfma_f32_16x16x32_bf16 v[76:79], v[128:131], v[202:205], 0
	v_mfma_f32_16x16x32_bf16 v[72:75], v[136:139], v[202:205], 0
	v_mfma_f32_16x16x32_bf16 v[124:127], v[132:135], v[164:167], v[124:127]
	v_mfma_f32_16x16x32_bf16 v[120:123], v[140:143], v[164:167], v[120:123]
	v_mfma_f32_16x16x32_bf16 v[108:111], v[132:135], v[190:193], v[108:111]
	v_mfma_f32_16x16x32_bf16 v[104:107], v[140:143], v[190:193], v[104:107]
	v_mfma_f32_16x16x32_bf16 v[92:95], v[132:135], v[198:201], v[92:95]
	v_mfma_f32_16x16x32_bf16 v[88:91], v[140:143], v[198:201], v[88:91]
	v_mfma_f32_16x16x32_bf16 v[76:79], v[132:135], v[206:209], v[76:79]
	v_mfma_f32_16x16x32_bf16 v[72:75], v[140:143], v[206:209], v[72:75]
	v_mfma_f32_16x16x32_bf16 v[116:119], v[144:147], v[160:163], 0
	v_mfma_f32_16x16x32_bf16 v[112:115], v[152:155], v[160:163], 0
	v_mfma_f32_16x16x32_bf16 v[100:103], v[144:147], v[186:189], 0
	v_mfma_f32_16x16x32_bf16 v[96:99], v[152:155], v[186:189], 0
	v_mfma_f32_16x16x32_bf16 v[84:87], v[144:147], v[194:197], 0
	v_mfma_f32_16x16x32_bf16 v[80:83], v[152:155], v[194:197], 0
	v_mfma_f32_16x16x32_bf16 v[68:71], v[144:147], v[202:205], 0
	v_mfma_f32_16x16x32_bf16 v[64:67], v[152:155], v[202:205], 0
	v_mfma_f32_16x16x32_bf16 v[116:119], v[148:151], v[164:167], v[116:119]
	v_mfma_f32_16x16x32_bf16 v[112:115], v[156:159], v[164:167], v[112:115]
	v_mfma_f32_16x16x32_bf16 v[100:103], v[148:151], v[190:193], v[100:103]
	v_mfma_f32_16x16x32_bf16 v[96:99], v[156:159], v[190:193], v[96:99]
	s_setprio 2
	s_barrier
	v_mfma_f32_16x16x32_bf16 v[84:87], v[148:151], v[198:201], v[84:87]
	v_mfma_f32_16x16x32_bf16 v[80:83], v[156:159], v[198:201], v[80:83]
	v_mfma_f32_16x16x32_bf16 v[68:71], v[148:151], v[206:209], v[68:71]
	v_mfma_f32_16x16x32_bf16 v[64:67], v[156:159], v[206:209], v[64:67]
	s_setprio 0
	s_add_i32 s8, s64, s37
	v_lshl_add_u64 v[178:179], s[50:51], 0, v[170:171]
	s_mov_b32 m0, s8
	ds_read_b128 v[160:163], v231 offset:16384
	ds_read_b128 v[164:167], v231 offset:17408
	ds_read_b128 v[186:189], v231 offset:18432
	ds_read_b128 v[190:193], v231 offset:19456
	ds_read_b128 v[194:197], v231 offset:20480
	ds_read_b128 v[198:201], v231 offset:21504
	ds_read_b128 v[202:205], v231 offset:22528
	ds_read_b128 v[206:209], v231 offset:23552
	global_load_lds_dwordx4 v[178:179], off
	s_add_i32 m0, s8, 0x2000
	s_add_u32 s8, s50, 0xb0000
	v_lshl_add_u64 v[210:211], s[50:51], 0, v[174:175]
	s_addc_u32 s9, s51, 0
	s_add_i32 s64, s65, s37
	global_load_lds_dwordx4 v[210:211], off
	v_lshl_add_u64 v[212:213], s[8:9], 0, v[170:171]
	s_mov_b32 m0, s64
	v_lshl_add_u64 v[220:221], s[52:53], 0, v[172:173]
	global_load_lds_dwordx4 v[212:213], off
	v_lshl_add_u64 v[212:213], s[8:9], 0, v[174:175]
	s_add_i32 m0, s64, 0x2000
	s_nop 0
	global_load_lds_dwordx4 v[212:213], off
	v_lshl_add_u64 v[212:213], s[52:53], 0, v[168:169]
	s_mov_b32 m0, s62
	s_nop 0
	global_load_lds_dwordx4 v[212:213], off
	s_mov_b32 m0, s63
	s_nop 0
	global_load_lds_dwordx4 v[220:221], off
	s_waitcnt vmcnt(8)
	s_waitcnt lgkmcnt(0)
	s_barrier
	s_setprio 1
	v_mfma_f32_16x16x32_bf16 v[60:63], v[128:131], v[160:163], 0
	v_mfma_f32_16x16x32_bf16 v[56:59], v[136:139], v[160:163], 0
	v_mfma_f32_16x16x32_bf16 v[44:47], v[128:131], v[186:189], 0
	v_mfma_f32_16x16x32_bf16 v[40:43], v[136:139], v[186:189], 0
	v_mfma_f32_16x16x32_bf16 v[28:31], v[128:131], v[194:197], 0
	v_mfma_f32_16x16x32_bf16 v[24:27], v[136:139], v[194:197], 0
	v_mfma_f32_16x16x32_bf16 v[12:15], v[128:131], v[202:205], 0
	v_mfma_f32_16x16x32_bf16 v[8:11], v[136:139], v[202:205], 0
	v_mfma_f32_16x16x32_bf16 v[60:63], v[132:135], v[164:167], v[60:63]
	v_mfma_f32_16x16x32_bf16 v[56:59], v[140:143], v[164:167], v[56:59]
	v_mfma_f32_16x16x32_bf16 v[44:47], v[132:135], v[190:193], v[44:47]
	v_mfma_f32_16x16x32_bf16 v[40:43], v[140:143], v[190:193], v[40:43]
	v_mfma_f32_16x16x32_bf16 v[28:31], v[132:135], v[198:201], v[28:31]
	v_mfma_f32_16x16x32_bf16 v[24:27], v[140:143], v[198:201], v[24:27]
	v_mfma_f32_16x16x32_bf16 v[12:15], v[132:135], v[206:209], v[12:15]
	v_mfma_f32_16x16x32_bf16 v[8:11], v[140:143], v[206:209], v[8:11]
	v_mfma_f32_16x16x32_bf16 v[52:55], v[144:147], v[160:163], 0
	v_mfma_f32_16x16x32_bf16 v[48:51], v[152:155], v[160:163], 0
	v_mfma_f32_16x16x32_bf16 v[36:39], v[144:147], v[186:189], 0
	v_mfma_f32_16x16x32_bf16 v[32:35], v[152:155], v[186:189], 0
	v_mfma_f32_16x16x32_bf16 v[20:23], v[144:147], v[194:197], 0
	v_mfma_f32_16x16x32_bf16 v[16:19], v[152:155], v[194:197], 0
	v_mfma_f32_16x16x32_bf16 v[4:7], v[144:147], v[202:205], 0
	v_mfma_f32_16x16x32_bf16 v[0:3], v[152:155], v[202:205], 0
	v_mfma_f32_16x16x32_bf16 v[52:55], v[148:151], v[164:167], v[52:55]
	v_mfma_f32_16x16x32_bf16 v[48:51], v[156:159], v[164:167], v[48:51]
	v_mfma_f32_16x16x32_bf16 v[36:39], v[148:151], v[190:193], v[36:39]
	v_mfma_f32_16x16x32_bf16 v[32:35], v[156:159], v[190:193], v[32:35]
	s_setprio 2
	s_barrier
	v_mfma_f32_16x16x32_bf16 v[20:23], v[148:151], v[198:201], v[20:23]
	v_mfma_f32_16x16x32_bf16 v[16:19], v[156:159], v[198:201], v[16:19]
	v_mfma_f32_16x16x32_bf16 v[4:7], v[148:151], v[206:209], v[4:7]
	v_mfma_f32_16x16x32_bf16 v[0:3], v[156:159], v[206:209], v[0:3]
	s_setprio 0
	s_add_i32 s64, 0, 0x18000
	s_add_i32 s65, 0, 0x1c000
	v_add_u32_e32 v140, s64, v228
	v_add_u32_e32 v156, s65, v228
	ds_read_b128 v[128:131], v140
	ds_read_b128 v[132:135], v140 offset:1024
	ds_read_b128 v[136:139], v140 offset:2048
	ds_read_b128 v[140:143], v140 offset:3072
	ds_read_b128 v[144:147], v156
	ds_read_b128 v[148:151], v156 offset:1024
	ds_read_b128 v[152:155], v156 offset:2048
	ds_read_b128 v[156:159], v156 offset:3072
	s_add_u32 s8, s52, 0xb0000
	s_addc_u32 s9, s53, 0
	s_mov_b32 m0, s68
	v_lshl_add_u64 v[222:223], s[8:9], 0, v[168:169]
	ds_read_b128 v[160:163], v231 offset:32768
	ds_read_b128 v[164:167], v231 offset:33792
	ds_read_b128 v[186:189], v231 offset:34816
	ds_read_b128 v[190:193], v231 offset:35840
	ds_read_b128 v[194:197], v231 offset:36864
	ds_read_b128 v[198:201], v231 offset:37888
	ds_read_b128 v[202:205], v231 offset:38912
	ds_read_b128 v[206:209], v231 offset:39936
	global_load_lds_dwordx4 v[222:223], off
	v_lshl_add_u64 v[222:223], s[8:9], 0, v[172:173]
	s_mov_b32 m0, s69
	s_nop 0
	global_load_lds_dwordx4 v[222:223], off
	s_waitcnt vmcnt(8)
	s_waitcnt lgkmcnt(0)
	s_barrier
	s_setprio 1
	v_mfma_f32_16x16x32_bf16 v[124:127], v[128:131], v[160:163], v[124:127]
	v_mfma_f32_16x16x32_bf16 v[120:123], v[136:139], v[160:163], v[120:123]
	v_mfma_f32_16x16x32_bf16 v[108:111], v[128:131], v[186:189], v[108:111]
	v_mfma_f32_16x16x32_bf16 v[104:107], v[136:139], v[186:189], v[104:107]
	v_mfma_f32_16x16x32_bf16 v[92:95], v[128:131], v[194:197], v[92:95]
	v_mfma_f32_16x16x32_bf16 v[88:91], v[136:139], v[194:197], v[88:91]
	v_mfma_f32_16x16x32_bf16 v[76:79], v[128:131], v[202:205], v[76:79]
	v_mfma_f32_16x16x32_bf16 v[72:75], v[136:139], v[202:205], v[72:75]
	v_mfma_f32_16x16x32_bf16 v[124:127], v[132:135], v[164:167], v[124:127]
	v_mfma_f32_16x16x32_bf16 v[120:123], v[140:143], v[164:167], v[120:123]
	v_mfma_f32_16x16x32_bf16 v[108:111], v[132:135], v[190:193], v[108:111]
	v_mfma_f32_16x16x32_bf16 v[104:107], v[140:143], v[190:193], v[104:107]
	v_mfma_f32_16x16x32_bf16 v[92:95], v[132:135], v[198:201], v[92:95]
	v_mfma_f32_16x16x32_bf16 v[88:91], v[140:143], v[198:201], v[88:91]
	v_mfma_f32_16x16x32_bf16 v[76:79], v[132:135], v[206:209], v[76:79]
	v_mfma_f32_16x16x32_bf16 v[72:75], v[140:143], v[206:209], v[72:75]
	v_mfma_f32_16x16x32_bf16 v[116:119], v[144:147], v[160:163], v[116:119]
	v_mfma_f32_16x16x32_bf16 v[112:115], v[152:155], v[160:163], v[112:115]
	v_mfma_f32_16x16x32_bf16 v[100:103], v[144:147], v[186:189], v[100:103]
	v_mfma_f32_16x16x32_bf16 v[96:99], v[152:155], v[186:189], v[96:99]
	v_mfma_f32_16x16x32_bf16 v[84:87], v[144:147], v[194:197], v[84:87]
	v_mfma_f32_16x16x32_bf16 v[80:83], v[152:155], v[194:197], v[80:83]
	v_mfma_f32_16x16x32_bf16 v[68:71], v[144:147], v[202:205], v[68:71]
	v_mfma_f32_16x16x32_bf16 v[64:67], v[152:155], v[202:205], v[64:67]
	v_mfma_f32_16x16x32_bf16 v[116:119], v[148:151], v[164:167], v[116:119]
	v_mfma_f32_16x16x32_bf16 v[112:115], v[156:159], v[164:167], v[112:115]
	v_mfma_f32_16x16x32_bf16 v[100:103], v[148:151], v[190:193], v[100:103]
	v_mfma_f32_16x16x32_bf16 v[96:99], v[156:159], v[190:193], v[96:99]
	s_setprio 2
	s_barrier
	v_mfma_f32_16x16x32_bf16 v[84:87], v[148:151], v[198:201], v[84:87]
	v_mfma_f32_16x16x32_bf16 v[80:83], v[156:159], v[198:201], v[80:83]
	v_mfma_f32_16x16x32_bf16 v[68:71], v[148:151], v[206:209], v[68:71]
	v_mfma_f32_16x16x32_bf16 v[64:67], v[156:159], v[206:209], v[64:67]
	s_setprio 0
	s_add_i32 s8, s64, s37
	v_lshl_add_u64 v[178:179], v[178:179], 0, s[34:35]
	s_mov_b32 m0, s8
	ds_read_b128 v[160:163], v231 offset:49152
	ds_read_b128 v[164:167], v231 offset:50176
	ds_read_b128 v[186:189], v231 offset:51200
	ds_read_b128 v[190:193], v231 offset:52224
	ds_read_b128 v[194:197], v231 offset:53248
	ds_read_b128 v[198:201], v231 offset:54272
	ds_read_b128 v[202:205], v231 offset:55296
	ds_read_b128 v[206:209], v231 offset:56320
	global_load_lds_dwordx4 v[178:179], off
	s_add_i32 m0, s8, 0x2000
	s_add_u32 s8, s50, 0xb0080
	v_lshl_add_u64 v[178:179], v[210:211], 0, s[34:35]
	s_addc_u32 s9, s51, 0
	s_add_i32 s50, s65, s37
	global_load_lds_dwordx4 v[178:179], off
	v_lshl_add_u64 v[178:179], s[8:9], 0, v[170:171]
	s_mov_b32 m0, s50
	s_nop 0
	global_load_lds_dwordx4 v[178:179], off
	v_lshl_add_u64 v[178:179], s[8:9], 0, v[174:175]
	s_add_i32 m0, s50, 0x2000
	s_nop 0
	global_load_lds_dwordx4 v[178:179], off
	v_lshl_add_u64 v[178:179], v[212:213], 0, s[34:35]
	s_mov_b32 m0, s73
	s_nop 0
	global_load_lds_dwordx4 v[178:179], off
	v_lshl_add_u64 v[178:179], v[220:221], 0, s[34:35]
	s_mov_b32 m0, s74
	s_nop 0
	global_load_lds_dwordx4 v[178:179], off
	s_waitcnt vmcnt(8)
	s_waitcnt lgkmcnt(0)
	s_barrier
	s_setprio 1
	v_mfma_f32_16x16x32_bf16 v[60:63], v[128:131], v[160:163], v[60:63]
	v_mfma_f32_16x16x32_bf16 v[56:59], v[136:139], v[160:163], v[56:59]
	v_mfma_f32_16x16x32_bf16 v[44:47], v[128:131], v[186:189], v[44:47]
	v_mfma_f32_16x16x32_bf16 v[40:43], v[136:139], v[186:189], v[40:43]
	v_mfma_f32_16x16x32_bf16 v[28:31], v[128:131], v[194:197], v[28:31]
	v_mfma_f32_16x16x32_bf16 v[24:27], v[136:139], v[194:197], v[24:27]
	v_mfma_f32_16x16x32_bf16 v[12:15], v[128:131], v[202:205], v[12:15]
	v_mfma_f32_16x16x32_bf16 v[8:11], v[136:139], v[202:205], v[8:11]
	v_mfma_f32_16x16x32_bf16 v[60:63], v[132:135], v[164:167], v[60:63]
	v_mfma_f32_16x16x32_bf16 v[56:59], v[140:143], v[164:167], v[56:59]
	v_mfma_f32_16x16x32_bf16 v[44:47], v[132:135], v[190:193], v[44:47]
	v_mfma_f32_16x16x32_bf16 v[40:43], v[140:143], v[190:193], v[40:43]
	v_mfma_f32_16x16x32_bf16 v[28:31], v[132:135], v[198:201], v[28:31]
	v_mfma_f32_16x16x32_bf16 v[24:27], v[140:143], v[198:201], v[24:27]
	v_mfma_f32_16x16x32_bf16 v[12:15], v[132:135], v[206:209], v[12:15]
	v_mfma_f32_16x16x32_bf16 v[8:11], v[140:143], v[206:209], v[8:11]
	v_mfma_f32_16x16x32_bf16 v[52:55], v[144:147], v[160:163], v[52:55]
	v_mfma_f32_16x16x32_bf16 v[48:51], v[152:155], v[160:163], v[48:51]
	v_mfma_f32_16x16x32_bf16 v[36:39], v[144:147], v[186:189], v[36:39]
	v_mfma_f32_16x16x32_bf16 v[32:35], v[152:155], v[186:189], v[32:35]
	v_mfma_f32_16x16x32_bf16 v[20:23], v[144:147], v[194:197], v[20:23]
	v_mfma_f32_16x16x32_bf16 v[16:19], v[152:155], v[194:197], v[16:19]
	v_mfma_f32_16x16x32_bf16 v[4:7], v[144:147], v[202:205], v[4:7]
	v_mfma_f32_16x16x32_bf16 v[0:3], v[152:155], v[202:205], v[0:3]
	v_mfma_f32_16x16x32_bf16 v[52:55], v[148:151], v[164:167], v[52:55]
	v_mfma_f32_16x16x32_bf16 v[48:51], v[156:159], v[164:167], v[48:51]
	v_mfma_f32_16x16x32_bf16 v[36:39], v[148:151], v[190:193], v[36:39]
	v_mfma_f32_16x16x32_bf16 v[32:35], v[156:159], v[190:193], v[32:35]
	s_setprio 2
	s_barrier
	v_mfma_f32_16x16x32_bf16 v[20:23], v[148:151], v[198:201], v[20:23]
	v_mfma_f32_16x16x32_bf16 v[16:19], v[156:159], v[198:201], v[16:19]
	v_mfma_f32_16x16x32_bf16 v[4:7], v[148:151], v[206:209], v[4:7]
	v_mfma_f32_16x16x32_bf16 v[0:3], v[156:159], v[206:209], v[0:3]
	s_setprio 0
	s_add_i32 s92, s92, 2
	s_add_u32 s44, s44, 0x100
	s_addc_u32 s55, s55, 0
	s_cmp_gt_u32 s92, 41
	s_mov_b64 s[8:9], s[40:41]
	s_cbranch_scc1 .Lpeel_exit_2

.Lpeel_exit_2:
	s_and_b64 vcc, exec, s[26:27]
	s_cbranch_vccz .LBB0_772
	s_barrier

.LBB0_862:
	s_add_i32 s27, s63, -2
	s_add_u32 vcc_lo, s40, 0x100
	s_addc_u32 vcc_hi, s41, 0
	s_mov_b32 s50, 0
	s_waitcnt vmcnt(0)
	s_add_i32 s64, s50, 2
	s_add_u32 s40, s8, 0x100
	s_addc_u32 s41, s9, 0
	s_add_i32 s65, 0, 0x10000
	s_cmp_eq_u32 s27, s50
	s_cselect_b32 s53, s29, s41
	s_cselect_b32 s52, s28, s40
	s_cselect_b32 s51, s39, vcc_hi
	s_cselect_b32 s50, s38, vcc_lo
	s_add_i32 s66, 0, 0x14000
	v_add_u32_e32 v140, s65, v228
	v_add_u32_e32 v156, s66, v228
	ds_read_b128 v[128:131], v140
	ds_read_b128 v[132:135], v140 offset:1024
	ds_read_b128 v[136:139], v140 offset:2048
	ds_read_b128 v[140:143], v140 offset:3072
	ds_read_b128 v[144:147], v156
	ds_read_b128 v[148:151], v156 offset:1024
	ds_read_b128 v[152:155], v156 offset:2048
	ds_read_b128 v[156:159], v156 offset:3072
	v_lshl_add_u64 v[178:179], s[8:9], 0, v[184:185]
	s_add_i32 m0, s74, 0xc000
	ds_read_b128 v[160:163], v232
	ds_read_b128 v[164:167], v232 offset:1024
	ds_read_b128 v[186:189], v232 offset:2048
	ds_read_b128 v[190:193], v232 offset:3072
	ds_read_b128 v[194:197], v232 offset:4096
	ds_read_b128 v[198:201], v232 offset:5120
	ds_read_b128 v[202:205], v232 offset:6144
	ds_read_b128 v[206:209], v232 offset:7168
	global_load_lds_dwordx4 v[178:179], off
	v_lshl_add_u64 v[178:179], s[8:9], 0, v[182:183]
	s_add_i32 m0, s74, 0xe000
	s_nop 0
	global_load_lds_dwordx4 v[178:179], off
	s_waitcnt vmcnt(8)
	s_waitcnt lgkmcnt(0)
	s_barrier
	s_setprio 1
	v_mfma_f32_16x16x32_bf16 v[124:127], v[128:131], v[160:163], 0
	v_mfma_f32_16x16x32_bf16 v[120:123], v[136:139], v[160:163], 0
	v_mfma_f32_16x16x32_bf16 v[108:111], v[128:131], v[186:189], 0
	v_mfma_f32_16x16x32_bf16 v[104:107], v[136:139], v[186:189], 0
	v_mfma_f32_16x16x32_bf16 v[92:95], v[128:131], v[194:197], 0
	v_mfma_f32_16x16x32_bf16 v[88:91], v[136:139], v[194:197], 0
	v_mfma_f32_16x16x32_bf16 v[76:79], v[128:131], v[202:205], 0
	v_mfma_f32_16x16x32_bf16 v[72:75], v[136:139], v[202:205], 0
	v_mfma_f32_16x16x32_bf16 v[124:127], v[132:135], v[164:167], v[124:127]
	v_mfma_f32_16x16x32_bf16 v[120:123], v[140:143], v[164:167], v[120:123]
	v_mfma_f32_16x16x32_bf16 v[108:111], v[132:135], v[190:193], v[108:111]
	v_mfma_f32_16x16x32_bf16 v[104:107], v[140:143], v[190:193], v[104:107]
	v_mfma_f32_16x16x32_bf16 v[92:95], v[132:135], v[198:201], v[92:95]
	v_mfma_f32_16x16x32_bf16 v[88:91], v[140:143], v[198:201], v[88:91]
	v_mfma_f32_16x16x32_bf16 v[76:79], v[132:135], v[206:209], v[76:79]
	v_mfma_f32_16x16x32_bf16 v[72:75], v[140:143], v[206:209], v[72:75]
	v_mfma_f32_16x16x32_bf16 v[116:119], v[144:147], v[160:163], 0
	v_mfma_f32_16x16x32_bf16 v[112:115], v[152:155], v[160:163], 0
	v_mfma_f32_16x16x32_bf16 v[100:103], v[144:147], v[186:189], 0
	v_mfma_f32_16x16x32_bf16 v[96:99], v[152:155], v[186:189], 0
	v_mfma_f32_16x16x32_bf16 v[84:87], v[144:147], v[194:197], 0
	v_mfma_f32_16x16x32_bf16 v[80:83], v[152:155], v[194:197], 0
	v_mfma_f32_16x16x32_bf16 v[68:71], v[144:147], v[202:205], 0
	v_mfma_f32_16x16x32_bf16 v[64:67], v[152:155], v[202:205], 0
	v_mfma_f32_16x16x32_bf16 v[116:119], v[148:151], v[164:167], v[116:119]
	v_mfma_f32_16x16x32_bf16 v[112:115], v[156:159], v[164:167], v[112:115]
	v_mfma_f32_16x16x32_bf16 v[100:103], v[148:151], v[190:193], v[100:103]
	v_mfma_f32_16x16x32_bf16 v[96:99], v[156:159], v[190:193], v[96:99]
	s_setprio 2
	s_barrier
	v_mfma_f32_16x16x32_bf16 v[84:87], v[148:151], v[198:201], v[84:87]
	v_mfma_f32_16x16x32_bf16 v[80:83], v[156:159], v[198:201], v[80:83]
	v_mfma_f32_16x16x32_bf16 v[68:71], v[148:151], v[206:209], v[68:71]
	v_mfma_f32_16x16x32_bf16 v[64:67], v[156:159], v[206:209], v[64:67]
	s_setprio 0
	s_add_i32 s8, s65, s72
	v_lshl_add_u64 v[178:179], s[50:51], 0, v[170:171]
	s_mov_b32 m0, s8
	ds_read_b128 v[160:163], v232 offset:16384
	ds_read_b128 v[164:167], v232 offset:17408
	ds_read_b128 v[186:189], v232 offset:18432
	ds_read_b128 v[190:193], v232 offset:19456
	ds_read_b128 v[194:197], v232 offset:20480
	ds_read_b128 v[198:201], v232 offset:21504
	ds_read_b128 v[202:205], v232 offset:22528
	ds_read_b128 v[206:209], v232 offset:23552
	global_load_lds_dwordx4 v[178:179], off
	s_add_i32 m0, s8, 0x2000
	s_add_u32 s8, s50, 0xb0000
	v_lshl_add_u64 v[210:211], s[50:51], 0, v[174:175]
	s_addc_u32 s9, s51, 0
	s_add_i32 s65, s66, s72
	global_load_lds_dwordx4 v[210:211], off
	v_lshl_add_u64 v[212:213], s[8:9], 0, v[170:171]
	s_mov_b32 m0, s65
	v_lshl_add_u64 v[220:221], s[52:53], 0, v[172:173]
	global_load_lds_dwordx4 v[212:213], off
	v_lshl_add_u64 v[212:213], s[8:9], 0, v[174:175]
	s_add_i32 m0, s65, 0x2000
	s_nop 0
	global_load_lds_dwordx4 v[212:213], off
	v_lshl_add_u64 v[212:213], s[52:53], 0, v[168:169]
	s_mov_b32 m0, s74
	s_nop 0
	global_load_lds_dwordx4 v[212:213], off
	s_mov_b32 m0, s75
	s_nop 0
	global_load_lds_dwordx4 v[220:221], off
	s_waitcnt vmcnt(8)
	s_waitcnt lgkmcnt(0)
	s_barrier
	s_setprio 1
	v_mfma_f32_16x16x32_bf16 v[60:63], v[128:131], v[160:163], 0
	v_mfma_f32_16x16x32_bf16 v[56:59], v[136:139], v[160:163], 0
	v_mfma_f32_16x16x32_bf16 v[44:47], v[128:131], v[186:189], 0
	v_mfma_f32_16x16x32_bf16 v[40:43], v[136:139], v[186:189], 0
	v_mfma_f32_16x16x32_bf16 v[28:31], v[128:131], v[194:197], 0
	v_mfma_f32_16x16x32_bf16 v[24:27], v[136:139], v[194:197], 0
	v_mfma_f32_16x16x32_bf16 v[12:15], v[128:131], v[202:205], 0
	v_mfma_f32_16x16x32_bf16 v[8:11], v[136:139], v[202:205], 0
	v_mfma_f32_16x16x32_bf16 v[60:63], v[132:135], v[164:167], v[60:63]
	v_mfma_f32_16x16x32_bf16 v[56:59], v[140:143], v[164:167], v[56:59]
	v_mfma_f32_16x16x32_bf16 v[44:47], v[132:135], v[190:193], v[44:47]
	v_mfma_f32_16x16x32_bf16 v[40:43], v[140:143], v[190:193], v[40:43]
	v_mfma_f32_16x16x32_bf16 v[28:31], v[132:135], v[198:201], v[28:31]
	v_mfma_f32_16x16x32_bf16 v[24:27], v[140:143], v[198:201], v[24:27]
	v_mfma_f32_16x16x32_bf16 v[12:15], v[132:135], v[206:209], v[12:15]
	v_mfma_f32_16x16x32_bf16 v[8:11], v[140:143], v[206:209], v[8:11]
	v_mfma_f32_16x16x32_bf16 v[52:55], v[144:147], v[160:163], 0
	v_mfma_f32_16x16x32_bf16 v[48:51], v[152:155], v[160:163], 0
	v_mfma_f32_16x16x32_bf16 v[36:39], v[144:147], v[186:189], 0
	v_mfma_f32_16x16x32_bf16 v[32:35], v[152:155], v[186:189], 0
	v_mfma_f32_16x16x32_bf16 v[20:23], v[144:147], v[194:197], 0
	v_mfma_f32_16x16x32_bf16 v[16:19], v[152:155], v[194:197], 0
	v_mfma_f32_16x16x32_bf16 v[4:7], v[144:147], v[202:205], 0
	v_mfma_f32_16x16x32_bf16 v[0:3], v[152:155], v[202:205], 0
	v_mfma_f32_16x16x32_bf16 v[52:55], v[148:151], v[164:167], v[52:55]
	v_mfma_f32_16x16x32_bf16 v[48:51], v[156:159], v[164:167], v[48:51]
	v_mfma_f32_16x16x32_bf16 v[36:39], v[148:151], v[190:193], v[36:39]
	v_mfma_f32_16x16x32_bf16 v[32:35], v[156:159], v[190:193], v[32:35]
	s_setprio 2
	s_barrier
	v_mfma_f32_16x16x32_bf16 v[20:23], v[148:151], v[198:201], v[20:23]
	v_mfma_f32_16x16x32_bf16 v[16:19], v[156:159], v[198:201], v[16:19]
	v_mfma_f32_16x16x32_bf16 v[4:7], v[148:151], v[206:209], v[4:7]
	v_mfma_f32_16x16x32_bf16 v[0:3], v[156:159], v[206:209], v[0:3]
	s_setprio 0
	s_add_i32 s65, 0, 0x18000
	s_add_i32 s66, 0, 0x1c000
	v_add_u32_e32 v140, s65, v228
	v_add_u32_e32 v156, s66, v228
	ds_read_b128 v[128:131], v140
	ds_read_b128 v[132:135], v140 offset:1024
	ds_read_b128 v[136:139], v140 offset:2048
	ds_read_b128 v[140:143], v140 offset:3072
	ds_read_b128 v[144:147], v156
	ds_read_b128 v[148:151], v156 offset:1024
	ds_read_b128 v[152:155], v156 offset:2048
	ds_read_b128 v[156:159], v156 offset:3072
	s_add_u32 s8, s52, 0xb0000
	s_addc_u32 s9, s53, 0
	s_mov_b32 m0, s80
	v_lshl_add_u64 v[222:223], s[8:9], 0, v[168:169]
	ds_read_b128 v[160:163], v232 offset:32768
	ds_read_b128 v[164:167], v232 offset:33792
	ds_read_b128 v[186:189], v232 offset:34816
	ds_read_b128 v[190:193], v232 offset:35840
	ds_read_b128 v[194:197], v232 offset:36864
	ds_read_b128 v[198:201], v232 offset:37888
	ds_read_b128 v[202:205], v232 offset:38912
	ds_read_b128 v[206:209], v232 offset:39936
	global_load_lds_dwordx4 v[222:223], off
	v_lshl_add_u64 v[222:223], s[8:9], 0, v[172:173]
	s_mov_b32 m0, s81
	s_nop 0
	global_load_lds_dwordx4 v[222:223], off
	s_waitcnt vmcnt(8)
	s_waitcnt lgkmcnt(0)
	s_barrier
	s_setprio 1
	v_mfma_f32_16x16x32_bf16 v[124:127], v[128:131], v[160:163], v[124:127]
	v_mfma_f32_16x16x32_bf16 v[120:123], v[136:139], v[160:163], v[120:123]
	v_mfma_f32_16x16x32_bf16 v[108:111], v[128:131], v[186:189], v[108:111]
	v_mfma_f32_16x16x32_bf16 v[104:107], v[136:139], v[186:189], v[104:107]
	v_mfma_f32_16x16x32_bf16 v[92:95], v[128:131], v[194:197], v[92:95]
	v_mfma_f32_16x16x32_bf16 v[88:91], v[136:139], v[194:197], v[88:91]
	v_mfma_f32_16x16x32_bf16 v[76:79], v[128:131], v[202:205], v[76:79]
	v_mfma_f32_16x16x32_bf16 v[72:75], v[136:139], v[202:205], v[72:75]
	v_mfma_f32_16x16x32_bf16 v[124:127], v[132:135], v[164:167], v[124:127]
	v_mfma_f32_16x16x32_bf16 v[120:123], v[140:143], v[164:167], v[120:123]
	v_mfma_f32_16x16x32_bf16 v[108:111], v[132:135], v[190:193], v[108:111]
	v_mfma_f32_16x16x32_bf16 v[104:107], v[140:143], v[190:193], v[104:107]
	v_mfma_f32_16x16x32_bf16 v[92:95], v[132:135], v[198:201], v[92:95]
	v_mfma_f32_16x16x32_bf16 v[88:91], v[140:143], v[198:201], v[88:91]
	v_mfma_f32_16x16x32_bf16 v[76:79], v[132:135], v[206:209], v[76:79]
	v_mfma_f32_16x16x32_bf16 v[72:75], v[140:143], v[206:209], v[72:75]
	v_mfma_f32_16x16x32_bf16 v[116:119], v[144:147], v[160:163], v[116:119]
	v_mfma_f32_16x16x32_bf16 v[112:115], v[152:155], v[160:163], v[112:115]
	v_mfma_f32_16x16x32_bf16 v[100:103], v[144:147], v[186:189], v[100:103]
	v_mfma_f32_16x16x32_bf16 v[96:99], v[152:155], v[186:189], v[96:99]
	v_mfma_f32_16x16x32_bf16 v[84:87], v[144:147], v[194:197], v[84:87]
	v_mfma_f32_16x16x32_bf16 v[80:83], v[152:155], v[194:197], v[80:83]
	v_mfma_f32_16x16x32_bf16 v[68:71], v[144:147], v[202:205], v[68:71]
	v_mfma_f32_16x16x32_bf16 v[64:67], v[152:155], v[202:205], v[64:67]
	v_mfma_f32_16x16x32_bf16 v[116:119], v[148:151], v[164:167], v[116:119]
	v_mfma_f32_16x16x32_bf16 v[112:115], v[156:159], v[164:167], v[112:115]
	v_mfma_f32_16x16x32_bf16 v[100:103], v[148:151], v[190:193], v[100:103]
	v_mfma_f32_16x16x32_bf16 v[96:99], v[156:159], v[190:193], v[96:99]
	s_setprio 2
	s_barrier
	v_mfma_f32_16x16x32_bf16 v[84:87], v[148:151], v[198:201], v[84:87]
	v_mfma_f32_16x16x32_bf16 v[80:83], v[156:159], v[198:201], v[80:83]
	v_mfma_f32_16x16x32_bf16 v[68:71], v[148:151], v[206:209], v[68:71]
	v_mfma_f32_16x16x32_bf16 v[64:67], v[156:159], v[206:209], v[64:67]
	s_setprio 0
	s_add_i32 s8, s65, s72
	v_lshl_add_u64 v[178:179], v[178:179], 0, s[34:35]
	s_mov_b32 m0, s8
	ds_read_b128 v[160:163], v232 offset:49152
	ds_read_b128 v[164:167], v232 offset:50176
	ds_read_b128 v[186:189], v232 offset:51200
	ds_read_b128 v[190:193], v232 offset:52224
	ds_read_b128 v[194:197], v232 offset:53248
	ds_read_b128 v[198:201], v232 offset:54272
	ds_read_b128 v[202:205], v232 offset:55296
	ds_read_b128 v[206:209], v232 offset:56320
	global_load_lds_dwordx4 v[178:179], off
	s_add_i32 m0, s8, 0x2000
	s_add_u32 s8, s50, 0xb0080
	v_lshl_add_u64 v[178:179], v[210:211], 0, s[34:35]
	s_addc_u32 s9, s51, 0
	s_add_i32 s50, s66, s72
	global_load_lds_dwordx4 v[178:179], off
	v_lshl_add_u64 v[178:179], s[8:9], 0, v[170:171]
	s_mov_b32 m0, s50
	s_nop 0
	global_load_lds_dwordx4 v[178:179], off
	v_lshl_add_u64 v[178:179], s[8:9], 0, v[174:175]
	s_add_i32 m0, s50, 0x2000
	s_nop 0
	global_load_lds_dwordx4 v[178:179], off
	v_lshl_add_u64 v[178:179], v[212:213], 0, s[34:35]
	s_mov_b32 m0, s83
	s_nop 0
	global_load_lds_dwordx4 v[178:179], off
	v_lshl_add_u64 v[178:179], v[220:221], 0, s[34:35]
	s_mov_b32 m0, s91
	s_nop 0
	global_load_lds_dwordx4 v[178:179], off
	s_waitcnt vmcnt(8)
	s_waitcnt lgkmcnt(0)
	s_barrier
	s_setprio 1
	v_mfma_f32_16x16x32_bf16 v[60:63], v[128:131], v[160:163], v[60:63]
	v_mfma_f32_16x16x32_bf16 v[56:59], v[136:139], v[160:163], v[56:59]
	v_mfma_f32_16x16x32_bf16 v[44:47], v[128:131], v[186:189], v[44:47]
	v_mfma_f32_16x16x32_bf16 v[40:43], v[136:139], v[186:189], v[40:43]
	v_mfma_f32_16x16x32_bf16 v[28:31], v[128:131], v[194:197], v[28:31]
	v_mfma_f32_16x16x32_bf16 v[24:27], v[136:139], v[194:197], v[24:27]
	v_mfma_f32_16x16x32_bf16 v[12:15], v[128:131], v[202:205], v[12:15]
	v_mfma_f32_16x16x32_bf16 v[8:11], v[136:139], v[202:205], v[8:11]
	v_mfma_f32_16x16x32_bf16 v[60:63], v[132:135], v[164:167], v[60:63]
	v_mfma_f32_16x16x32_bf16 v[56:59], v[140:143], v[164:167], v[56:59]
	v_mfma_f32_16x16x32_bf16 v[44:47], v[132:135], v[190:193], v[44:47]
	v_mfma_f32_16x16x32_bf16 v[40:43], v[140:143], v[190:193], v[40:43]
	v_mfma_f32_16x16x32_bf16 v[28:31], v[132:135], v[198:201], v[28:31]
	v_mfma_f32_16x16x32_bf16 v[24:27], v[140:143], v[198:201], v[24:27]
	v_mfma_f32_16x16x32_bf16 v[12:15], v[132:135], v[206:209], v[12:15]
	v_mfma_f32_16x16x32_bf16 v[8:11], v[140:143], v[206:209], v[8:11]
	v_mfma_f32_16x16x32_bf16 v[52:55], v[144:147], v[160:163], v[52:55]
	v_mfma_f32_16x16x32_bf16 v[48:51], v[152:155], v[160:163], v[48:51]
	v_mfma_f32_16x16x32_bf16 v[36:39], v[144:147], v[186:189], v[36:39]
	v_mfma_f32_16x16x32_bf16 v[32:35], v[152:155], v[186:189], v[32:35]
	v_mfma_f32_16x16x32_bf16 v[20:23], v[144:147], v[194:197], v[20:23]
	v_mfma_f32_16x16x32_bf16 v[16:19], v[152:155], v[194:197], v[16:19]
	v_mfma_f32_16x16x32_bf16 v[4:7], v[144:147], v[202:205], v[4:7]
	v_mfma_f32_16x16x32_bf16 v[0:3], v[152:155], v[202:205], v[0:3]
	v_mfma_f32_16x16x32_bf16 v[52:55], v[148:151], v[164:167], v[52:55]
	v_mfma_f32_16x16x32_bf16 v[48:51], v[156:159], v[164:167], v[48:51]
	v_mfma_f32_16x16x32_bf16 v[36:39], v[148:151], v[190:193], v[36:39]
	v_mfma_f32_16x16x32_bf16 v[32:35], v[156:159], v[190:193], v[32:35]
	s_setprio 2
	s_barrier
	v_mfma_f32_16x16x32_bf16 v[20:23], v[148:151], v[198:201], v[20:23]
	v_mfma_f32_16x16x32_bf16 v[16:19], v[156:159], v[198:201], v[16:19]
	v_mfma_f32_16x16x32_bf16 v[4:7], v[148:151], v[206:209], v[4:7]
	v_mfma_f32_16x16x32_bf16 v[0:3], v[156:159], v[206:209], v[0:3]
	s_setprio 0
	s_add_u32 vcc_lo, vcc_lo, 0x100
	s_addc_u32 vcc_hi, vcc_hi, 0
	s_cmp_ge_i32 s64, s63
	s_mov_b64 s[8:9], s[40:41]
	s_mov_b32 s50, s64
	s_cbranch_scc1 .Lpeel_exit_3

.Lpeel_exit_3:
	s_and_b64 vcc, exec, s[22:23]
	s_cbranch_vccz .LBB0_866

.LBB0_952:
	s_add_u32 s44, s38, 0x180
	s_addc_u32 s53, s39, 0
	s_mov_b32 s83, -2
	s_waitcnt vmcnt(0)
	s_add_u32 s38, s8, 0x180
	s_addc_u32 s39, s9, 0
	s_add_i32 s64, 0, 0x10000
	s_cmp_eq_u32 s83, 12
	s_cselect_b32 s51, s1, s39
	s_cselect_b32 s50, s0, s38
	s_cselect_b32 s41, s29, s53
	s_cselect_b32 s40, s28, s44
	s_add_i32 s65, 0, 0x14000
	v_add_u32_e32 v68, s64, v228
	v_add_u32_e32 v156, s65, v228
	ds_read_b128 v[56:59], v68
	ds_read_b128 v[60:63], v68 offset:1024
	ds_read_b128 v[64:67], v68 offset:2048
	ds_read_b128 v[68:71], v68 offset:3072
	ds_read_b128 v[144:147], v156
	ds_read_b128 v[148:151], v156 offset:1024
	ds_read_b128 v[152:155], v156 offset:2048
	ds_read_b128 v[156:159], v156 offset:3072
	v_lshl_add_u64 v[178:179], s[8:9], 0, v[192:193]
	s_add_i32 m0, s60, 0xc000
	ds_read_b128 v[160:163], v231
	ds_read_b128 v[164:167], v231 offset:1024
	ds_read_b128 v[168:171], v231 offset:2048
	ds_read_b128 v[172:175], v231 offset:3072
	ds_read_b128 v[194:197], v231 offset:4096
	ds_read_b128 v[198:201], v231 offset:5120
	ds_read_b128 v[202:205], v231 offset:6144
	ds_read_b128 v[206:209], v231 offset:7168
	global_load_lds_dwordx4 v[178:179], off
	v_lshl_add_u64 v[178:179], s[8:9], 0, v[190:191]
	s_add_i32 m0, s60, 0xe000
	s_nop 0
	global_load_lds_dwordx4 v[178:179], off
	s_waitcnt vmcnt(8)
	s_waitcnt lgkmcnt(0)
	s_barrier
	s_setprio 1
	v_mfma_f32_16x16x32_bf16 v[140:143], v[56:59], v[160:163], 0
	v_mfma_f32_16x16x32_bf16 v[136:139], v[64:67], v[160:163], 0
	v_mfma_f32_16x16x32_bf16 v[128:131], v[56:59], v[168:171], 0
	v_mfma_f32_16x16x32_bf16 v[120:123], v[64:67], v[168:171], 0
	v_mfma_f32_16x16x32_bf16 v[108:111], v[56:59], v[194:197], 0
	v_mfma_f32_16x16x32_bf16 v[104:107], v[64:67], v[194:197], 0
	v_mfma_f32_16x16x32_bf16 v[92:95], v[56:59], v[202:205], 0
	v_mfma_f32_16x16x32_bf16 v[88:91], v[64:67], v[202:205], 0
	v_mfma_f32_16x16x32_bf16 v[140:143], v[60:63], v[164:167], v[140:143]
	v_mfma_f32_16x16x32_bf16 v[136:139], v[68:71], v[164:167], v[136:139]
	v_mfma_f32_16x16x32_bf16 v[128:131], v[60:63], v[172:175], v[128:131]
	v_mfma_f32_16x16x32_bf16 v[120:123], v[68:71], v[172:175], v[120:123]
	v_mfma_f32_16x16x32_bf16 v[108:111], v[60:63], v[198:201], v[108:111]
	v_mfma_f32_16x16x32_bf16 v[104:107], v[68:71], v[198:201], v[104:107]
	v_mfma_f32_16x16x32_bf16 v[92:95], v[60:63], v[206:209], v[92:95]
	v_mfma_f32_16x16x32_bf16 v[88:91], v[68:71], v[206:209], v[88:91]
	v_mfma_f32_16x16x32_bf16 v[132:135], v[144:147], v[160:163], 0
	v_mfma_f32_16x16x32_bf16 v[124:127], v[152:155], v[160:163], 0
	v_mfma_f32_16x16x32_bf16 v[116:119], v[144:147], v[168:171], 0
	v_mfma_f32_16x16x32_bf16 v[112:115], v[152:155], v[168:171], 0
	v_mfma_f32_16x16x32_bf16 v[100:103], v[144:147], v[194:197], 0
	v_mfma_f32_16x16x32_bf16 v[96:99], v[152:155], v[194:197], 0
	v_mfma_f32_16x16x32_bf16 v[84:87], v[144:147], v[202:205], 0
	v_mfma_f32_16x16x32_bf16 v[80:83], v[152:155], v[202:205], 0
	v_mfma_f32_16x16x32_bf16 v[132:135], v[148:151], v[164:167], v[132:135]
	v_mfma_f32_16x16x32_bf16 v[124:127], v[156:159], v[164:167], v[124:127]
	v_mfma_f32_16x16x32_bf16 v[116:119], v[148:151], v[172:175], v[116:119]
	v_mfma_f32_16x16x32_bf16 v[112:115], v[156:159], v[172:175], v[112:115]
	s_setprio 2
	s_barrier
	v_mfma_f32_16x16x32_bf16 v[100:103], v[148:151], v[198:201], v[100:103]
	v_mfma_f32_16x16x32_bf16 v[96:99], v[156:159], v[198:201], v[96:99]
	v_mfma_f32_16x16x32_bf16 v[84:87], v[148:151], v[206:209], v[84:87]
	v_mfma_f32_16x16x32_bf16 v[80:83], v[156:159], v[206:209], v[80:83]
	s_setprio 0
	s_add_i32 s8, s64, s37
	v_lshl_add_u64 v[178:179], s[40:41], 0, v[184:185]
	s_mov_b32 m0, s8
	ds_read_b128 v[160:163], v231 offset:16384
	ds_read_b128 v[164:167], v231 offset:17408
	ds_read_b128 v[168:171], v231 offset:18432
	ds_read_b128 v[172:175], v231 offset:19456
	ds_read_b128 v[194:197], v231 offset:20480
	ds_read_b128 v[198:201], v231 offset:21504
	ds_read_b128 v[202:205], v231 offset:22528
	ds_read_b128 v[206:209], v231 offset:23552
	global_load_lds_dwordx4 v[178:179], off
	s_add_i32 m0, s8, 0x2000
	s_add_u32 s8, s40, 0x60000
	v_lshl_add_u64 v[210:211], s[40:41], 0, v[188:189]
	s_addc_u32 s9, s41, 0
	s_add_i32 s64, s65, s37
	global_load_lds_dwordx4 v[210:211], off
	v_lshl_add_u64 v[212:213], s[8:9], 0, v[184:185]
	s_mov_b32 m0, s64
	v_lshl_add_u64 v[220:221], s[50:51], 0, v[186:187]
	global_load_lds_dwordx4 v[212:213], off
	v_lshl_add_u64 v[212:213], s[8:9], 0, v[188:189]
	s_add_i32 m0, s64, 0x2000
	s_nop 0
	global_load_lds_dwordx4 v[212:213], off
	v_lshl_add_u64 v[212:213], s[50:51], 0, v[182:183]
	s_mov_b32 m0, s60
	s_nop 0
	global_load_lds_dwordx4 v[212:213], off
	s_mov_b32 m0, s61
	s_nop 0
	global_load_lds_dwordx4 v[220:221], off
	s_waitcnt vmcnt(8)
	s_waitcnt lgkmcnt(0)
	s_barrier
	s_setprio 1
	v_mfma_f32_16x16x32_bf16 v[76:79], v[56:59], v[160:163], 0
	v_mfma_f32_16x16x32_bf16 v[72:75], v[64:67], v[160:163], 0
	v_mfma_f32_16x16x32_bf16 v[44:47], v[56:59], v[168:171], 0
	v_mfma_f32_16x16x32_bf16 v[40:43], v[64:67], v[168:171], 0
	v_mfma_f32_16x16x32_bf16 v[28:31], v[56:59], v[194:197], 0
	v_mfma_f32_16x16x32_bf16 v[24:27], v[64:67], v[194:197], 0
	v_mfma_f32_16x16x32_bf16 v[12:15], v[56:59], v[202:205], 0
	v_mfma_f32_16x16x32_bf16 v[8:11], v[64:67], v[202:205], 0
	v_mfma_f32_16x16x32_bf16 v[76:79], v[60:63], v[164:167], v[76:79]
	v_mfma_f32_16x16x32_bf16 v[72:75], v[68:71], v[164:167], v[72:75]
	v_mfma_f32_16x16x32_bf16 v[44:47], v[60:63], v[172:175], v[44:47]
	v_mfma_f32_16x16x32_bf16 v[40:43], v[68:71], v[172:175], v[40:43]
	v_mfma_f32_16x16x32_bf16 v[28:31], v[60:63], v[198:201], v[28:31]
	v_mfma_f32_16x16x32_bf16 v[24:27], v[68:71], v[198:201], v[24:27]
	v_mfma_f32_16x16x32_bf16 v[12:15], v[60:63], v[206:209], v[12:15]
	v_mfma_f32_16x16x32_bf16 v[8:11], v[68:71], v[206:209], v[8:11]
	v_mfma_f32_16x16x32_bf16 v[52:55], v[144:147], v[160:163], 0
	v_mfma_f32_16x16x32_bf16 v[48:51], v[152:155], v[160:163], 0
	v_mfma_f32_16x16x32_bf16 v[36:39], v[144:147], v[168:171], 0
	v_mfma_f32_16x16x32_bf16 v[32:35], v[152:155], v[168:171], 0
	v_mfma_f32_16x16x32_bf16 v[20:23], v[144:147], v[194:197], 0
	v_mfma_f32_16x16x32_bf16 v[16:19], v[152:155], v[194:197], 0
	v_mfma_f32_16x16x32_bf16 v[4:7], v[144:147], v[202:205], 0
	v_mfma_f32_16x16x32_bf16 v[0:3], v[152:155], v[202:205], 0
	v_mfma_f32_16x16x32_bf16 v[52:55], v[148:151], v[164:167], v[52:55]
	v_mfma_f32_16x16x32_bf16 v[48:51], v[156:159], v[164:167], v[48:51]
	v_mfma_f32_16x16x32_bf16 v[36:39], v[148:151], v[172:175], v[36:39]
	v_mfma_f32_16x16x32_bf16 v[32:35], v[156:159], v[172:175], v[32:35]
	s_setprio 2
	s_barrier
	v_mfma_f32_16x16x32_bf16 v[20:23], v[148:151], v[198:201], v[20:23]
	v_mfma_f32_16x16x32_bf16 v[16:19], v[156:159], v[198:201], v[16:19]
	v_mfma_f32_16x16x32_bf16 v[4:7], v[148:151], v[206:209], v[4:7]
	v_mfma_f32_16x16x32_bf16 v[0:3], v[156:159], v[206:209], v[0:3]
	s_setprio 0
	s_add_i32 s64, 0, 0x18000
	s_add_i32 s65, 0, 0x1c000
	v_add_u32_e32 v68, s64, v228
	v_add_u32_e32 v156, s65, v228
	ds_read_b128 v[56:59], v68
	ds_read_b128 v[60:63], v68 offset:1024
	ds_read_b128 v[64:67], v68 offset:2048
	ds_read_b128 v[68:71], v68 offset:3072
	ds_read_b128 v[144:147], v156
	ds_read_b128 v[148:151], v156 offset:1024
	ds_read_b128 v[152:155], v156 offset:2048
	ds_read_b128 v[156:159], v156 offset:3072
	s_add_u32 s8, s50, 0x60000
	s_addc_u32 s9, s51, 0
	s_mov_b32 m0, s62
	v_lshl_add_u64 v[222:223], s[8:9], 0, v[182:183]
	ds_read_b128 v[160:163], v231 offset:32768
	ds_read_b128 v[164:167], v231 offset:33792
	ds_read_b128 v[168:171], v231 offset:34816
	ds_read_b128 v[172:175], v231 offset:35840
	ds_read_b128 v[194:197], v231 offset:36864
	ds_read_b128 v[198:201], v231 offset:37888
	ds_read_b128 v[202:205], v231 offset:38912
	ds_read_b128 v[206:209], v231 offset:39936
	global_load_lds_dwordx4 v[222:223], off
	v_lshl_add_u64 v[222:223], s[8:9], 0, v[186:187]
	s_mov_b32 m0, s63
	s_nop 0
	global_load_lds_dwordx4 v[222:223], off
	s_waitcnt vmcnt(8)
	s_waitcnt lgkmcnt(0)
	s_barrier
	s_setprio 1
	v_mfma_f32_16x16x32_bf16 v[140:143], v[56:59], v[160:163], v[140:143]
	v_mfma_f32_16x16x32_bf16 v[136:139], v[64:67], v[160:163], v[136:139]
	v_mfma_f32_16x16x32_bf16 v[128:131], v[56:59], v[168:171], v[128:131]
	v_mfma_f32_16x16x32_bf16 v[120:123], v[64:67], v[168:171], v[120:123]
	v_mfma_f32_16x16x32_bf16 v[108:111], v[56:59], v[194:197], v[108:111]
	v_mfma_f32_16x16x32_bf16 v[104:107], v[64:67], v[194:197], v[104:107]
	v_mfma_f32_16x16x32_bf16 v[92:95], v[56:59], v[202:205], v[92:95]
	v_mfma_f32_16x16x32_bf16 v[88:91], v[64:67], v[202:205], v[88:91]
	v_mfma_f32_16x16x32_bf16 v[140:143], v[60:63], v[164:167], v[140:143]
	v_mfma_f32_16x16x32_bf16 v[136:139], v[68:71], v[164:167], v[136:139]
	v_mfma_f32_16x16x32_bf16 v[128:131], v[60:63], v[172:175], v[128:131]
	v_mfma_f32_16x16x32_bf16 v[120:123], v[68:71], v[172:175], v[120:123]
	v_mfma_f32_16x16x32_bf16 v[108:111], v[60:63], v[198:201], v[108:111]
	v_mfma_f32_16x16x32_bf16 v[104:107], v[68:71], v[198:201], v[104:107]
	v_mfma_f32_16x16x32_bf16 v[92:95], v[60:63], v[206:209], v[92:95]
	v_mfma_f32_16x16x32_bf16 v[88:91], v[68:71], v[206:209], v[88:91]
	v_mfma_f32_16x16x32_bf16 v[132:135], v[144:147], v[160:163], v[132:135]
	v_mfma_f32_16x16x32_bf16 v[124:127], v[152:155], v[160:163], v[124:127]
	v_mfma_f32_16x16x32_bf16 v[116:119], v[144:147], v[168:171], v[116:119]
	v_mfma_f32_16x16x32_bf16 v[112:115], v[152:155], v[168:171], v[112:115]
	v_mfma_f32_16x16x32_bf16 v[100:103], v[144:147], v[194:197], v[100:103]
	v_mfma_f32_16x16x32_bf16 v[96:99], v[152:155], v[194:197], v[96:99]
	v_mfma_f32_16x16x32_bf16 v[84:87], v[144:147], v[202:205], v[84:87]
	v_mfma_f32_16x16x32_bf16 v[80:83], v[152:155], v[202:205], v[80:83]
	v_mfma_f32_16x16x32_bf16 v[132:135], v[148:151], v[164:167], v[132:135]
	v_mfma_f32_16x16x32_bf16 v[124:127], v[156:159], v[164:167], v[124:127]
	v_mfma_f32_16x16x32_bf16 v[116:119], v[148:151], v[172:175], v[116:119]
	v_mfma_f32_16x16x32_bf16 v[112:115], v[156:159], v[172:175], v[112:115]
	s_setprio 2
	s_barrier
	v_mfma_f32_16x16x32_bf16 v[100:103], v[148:151], v[198:201], v[100:103]
	v_mfma_f32_16x16x32_bf16 v[96:99], v[156:159], v[198:201], v[96:99]
	v_mfma_f32_16x16x32_bf16 v[84:87], v[148:151], v[206:209], v[84:87]
	v_mfma_f32_16x16x32_bf16 v[80:83], v[156:159], v[206:209], v[80:83]
	s_setprio 0
	s_add_i32 s8, s64, s37
	v_lshl_add_u64 v[178:179], v[178:179], 0, s[34:35]
	s_mov_b32 m0, s8
	ds_read_b128 v[160:163], v231 offset:49152
	ds_read_b128 v[164:167], v231 offset:50176
	ds_read_b128 v[168:171], v231 offset:51200
	ds_read_b128 v[172:175], v231 offset:52224
	ds_read_b128 v[194:197], v231 offset:53248
	ds_read_b128 v[198:201], v231 offset:54272
	ds_read_b128 v[202:205], v231 offset:55296
	ds_read_b128 v[206:209], v231 offset:56320
	global_load_lds_dwordx4 v[178:179], off
	s_add_i32 m0, s8, 0x2000
	s_add_u32 s8, s40, 0x60080
	v_lshl_add_u64 v[178:179], v[210:211], 0, s[34:35]
	s_addc_u32 s9, s41, 0
	s_add_i32 s40, s65, s37
	global_load_lds_dwordx4 v[178:179], off
	v_lshl_add_u64 v[178:179], s[8:9], 0, v[184:185]
	s_mov_b32 m0, s40
	s_nop 0
	global_load_lds_dwordx4 v[178:179], off
	v_lshl_add_u64 v[178:179], s[8:9], 0, v[188:189]
	s_add_i32 m0, s40, 0x2000
	s_nop 0
	global_load_lds_dwordx4 v[178:179], off
	v_lshl_add_u64 v[178:179], v[212:213], 0, s[34:35]
	s_mov_b32 m0, s69
	s_nop 0
	global_load_lds_dwordx4 v[178:179], off
	v_lshl_add_u64 v[178:179], v[220:221], 0, s[34:35]
	s_mov_b32 m0, s72
	s_nop 0
	global_load_lds_dwordx4 v[178:179], off
	s_waitcnt vmcnt(8)
	s_waitcnt lgkmcnt(0)
	s_barrier
	s_setprio 1
	v_mfma_f32_16x16x32_bf16 v[76:79], v[56:59], v[160:163], v[76:79]
	v_mfma_f32_16x16x32_bf16 v[72:75], v[64:67], v[160:163], v[72:75]
	v_mfma_f32_16x16x32_bf16 v[44:47], v[56:59], v[168:171], v[44:47]
	v_mfma_f32_16x16x32_bf16 v[40:43], v[64:67], v[168:171], v[40:43]
	v_mfma_f32_16x16x32_bf16 v[28:31], v[56:59], v[194:197], v[28:31]
	v_mfma_f32_16x16x32_bf16 v[24:27], v[64:67], v[194:197], v[24:27]
	v_mfma_f32_16x16x32_bf16 v[12:15], v[56:59], v[202:205], v[12:15]
	v_mfma_f32_16x16x32_bf16 v[8:11], v[64:67], v[202:205], v[8:11]
	v_mfma_f32_16x16x32_bf16 v[76:79], v[60:63], v[164:167], v[76:79]
	v_mfma_f32_16x16x32_bf16 v[72:75], v[68:71], v[164:167], v[72:75]
	v_mfma_f32_16x16x32_bf16 v[44:47], v[60:63], v[172:175], v[44:47]
	v_mfma_f32_16x16x32_bf16 v[40:43], v[68:71], v[172:175], v[40:43]
	v_mfma_f32_16x16x32_bf16 v[28:31], v[60:63], v[198:201], v[28:31]
	v_mfma_f32_16x16x32_bf16 v[24:27], v[68:71], v[198:201], v[24:27]
	v_mfma_f32_16x16x32_bf16 v[12:15], v[60:63], v[206:209], v[12:15]
	v_mfma_f32_16x16x32_bf16 v[8:11], v[68:71], v[206:209], v[8:11]
	v_mfma_f32_16x16x32_bf16 v[52:55], v[144:147], v[160:163], v[52:55]
	v_mfma_f32_16x16x32_bf16 v[48:51], v[152:155], v[160:163], v[48:51]
	v_mfma_f32_16x16x32_bf16 v[36:39], v[144:147], v[168:171], v[36:39]
	v_mfma_f32_16x16x32_bf16 v[32:35], v[152:155], v[168:171], v[32:35]
	v_mfma_f32_16x16x32_bf16 v[20:23], v[144:147], v[194:197], v[20:23]
	v_mfma_f32_16x16x32_bf16 v[16:19], v[152:155], v[194:197], v[16:19]
	v_mfma_f32_16x16x32_bf16 v[4:7], v[144:147], v[202:205], v[4:7]
	v_mfma_f32_16x16x32_bf16 v[0:3], v[152:155], v[202:205], v[0:3]
	v_mfma_f32_16x16x32_bf16 v[52:55], v[148:151], v[164:167], v[52:55]
	v_mfma_f32_16x16x32_bf16 v[48:51], v[156:159], v[164:167], v[48:51]
	v_mfma_f32_16x16x32_bf16 v[36:39], v[148:151], v[172:175], v[36:39]
	v_mfma_f32_16x16x32_bf16 v[32:35], v[156:159], v[172:175], v[32:35]
	s_setprio 2
	s_barrier
	v_mfma_f32_16x16x32_bf16 v[20:23], v[148:151], v[198:201], v[20:23]
	v_mfma_f32_16x16x32_bf16 v[16:19], v[156:159], v[198:201], v[16:19]
	v_mfma_f32_16x16x32_bf16 v[4:7], v[148:151], v[206:209], v[4:7]
	v_mfma_f32_16x16x32_bf16 v[0:3], v[156:159], v[206:209], v[0:3]
	s_setprio 0
	s_add_i32 s83, s83, 2
	s_add_u32 s44, s44, 0x180
	s_addc_u32 s53, s53, 0
	s_cmp_gt_u32 s83, 13
	s_mov_b64 s[8:9], s[38:39]
	s_cbranch_scc1 .Lpeel_exit_4

.Lpeel_exit_4:
	s_and_b64 vcc, exec, s[24:25]
	s_cbranch_vccz .LBB0_956
	s_barrier

.LBB0_1045:
	s_add_i32 s25, s63, -2
	s_add_u32 s93, s38, 0x180
	s_addc_u32 s94, s39, 0
	s_mov_b32 s40, 0
	s_waitcnt vmcnt(0)
	s_add_i32 s64, s40, 2
	s_add_u32 s38, s8, 0x180
	s_addc_u32 s39, s9, 0
	s_add_i32 s65, 0, 0x10000
	s_cmp_eq_u32 s25, s40
	s_cselect_b32 s51, s27, s39
	s_cselect_b32 s50, s26, s38
	s_cselect_b32 s41, s29, s94
	s_cselect_b32 s40, s28, s93
	s_add_i32 s66, 0, 0x14000
	v_add_u32_e32 v108, s65, v228
	v_add_u32_e32 v156, s66, v228
	ds_read_b128 v[88:91], v108
	ds_read_b128 v[92:95], v108 offset:1024
	ds_read_b128 v[104:107], v108 offset:2048
	ds_read_b128 v[108:111], v108 offset:3072
	ds_read_b128 v[144:147], v156
	ds_read_b128 v[148:151], v156 offset:1024
	ds_read_b128 v[152:155], v156 offset:2048
	ds_read_b128 v[156:159], v156 offset:3072
	v_lshl_add_u64 v[178:179], s[8:9], 0, v[192:193]
	s_add_i32 m0, s72, 0xc000
	ds_read_b128 v[160:163], v232
	ds_read_b128 v[164:167], v232 offset:1024
	ds_read_b128 v[168:171], v232 offset:2048
	ds_read_b128 v[172:175], v232 offset:3072
	ds_read_b128 v[194:197], v232 offset:4096
	ds_read_b128 v[198:201], v232 offset:5120
	ds_read_b128 v[202:205], v232 offset:6144
	ds_read_b128 v[206:209], v232 offset:7168
	global_load_lds_dwordx4 v[178:179], off
	v_lshl_add_u64 v[178:179], s[8:9], 0, v[190:191]
	s_add_i32 m0, s72, 0xe000
	s_nop 0
	global_load_lds_dwordx4 v[178:179], off
	s_waitcnt vmcnt(8)
	s_waitcnt lgkmcnt(0)
	s_barrier
	s_setprio 1
	v_mfma_f32_16x16x32_bf16 v[140:143], v[88:91], v[160:163], 0
	v_mfma_f32_16x16x32_bf16 v[136:139], v[104:107], v[160:163], 0
	v_mfma_f32_16x16x32_bf16 v[124:127], v[88:91], v[168:171], 0
	v_mfma_f32_16x16x32_bf16 v[120:123], v[104:107], v[168:171], 0
	v_mfma_f32_16x16x32_bf16 v[100:103], v[88:91], v[194:197], 0
	v_mfma_f32_16x16x32_bf16 v[96:99], v[104:107], v[194:197], 0
	v_mfma_f32_16x16x32_bf16 v[76:79], v[88:91], v[202:205], 0
	v_mfma_f32_16x16x32_bf16 v[72:75], v[104:107], v[202:205], 0
	v_mfma_f32_16x16x32_bf16 v[140:143], v[92:95], v[164:167], v[140:143]
	v_mfma_f32_16x16x32_bf16 v[136:139], v[108:111], v[164:167], v[136:139]
	v_mfma_f32_16x16x32_bf16 v[124:127], v[92:95], v[172:175], v[124:127]
	v_mfma_f32_16x16x32_bf16 v[120:123], v[108:111], v[172:175], v[120:123]
	v_mfma_f32_16x16x32_bf16 v[100:103], v[92:95], v[198:201], v[100:103]
	v_mfma_f32_16x16x32_bf16 v[96:99], v[108:111], v[198:201], v[96:99]
	v_mfma_f32_16x16x32_bf16 v[76:79], v[92:95], v[206:209], v[76:79]
	v_mfma_f32_16x16x32_bf16 v[72:75], v[108:111], v[206:209], v[72:75]
	v_mfma_f32_16x16x32_bf16 v[132:135], v[144:147], v[160:163], 0
	v_mfma_f32_16x16x32_bf16 v[128:131], v[152:155], v[160:163], 0
	v_mfma_f32_16x16x32_bf16 v[116:119], v[144:147], v[168:171], 0
	v_mfma_f32_16x16x32_bf16 v[112:115], v[152:155], v[168:171], 0
	v_mfma_f32_16x16x32_bf16 v[84:87], v[144:147], v[194:197], 0
	v_mfma_f32_16x16x32_bf16 v[80:83], v[152:155], v[194:197], 0
	v_mfma_f32_16x16x32_bf16 v[68:71], v[144:147], v[202:205], 0
	v_mfma_f32_16x16x32_bf16 v[64:67], v[152:155], v[202:205], 0
	v_mfma_f32_16x16x32_bf16 v[132:135], v[148:151], v[164:167], v[132:135]
	v_mfma_f32_16x16x32_bf16 v[128:131], v[156:159], v[164:167], v[128:131]
	v_mfma_f32_16x16x32_bf16 v[116:119], v[148:151], v[172:175], v[116:119]
	v_mfma_f32_16x16x32_bf16 v[112:115], v[156:159], v[172:175], v[112:115]
	s_setprio 2
	s_barrier
	v_mfma_f32_16x16x32_bf16 v[84:87], v[148:151], v[198:201], v[84:87]
	v_mfma_f32_16x16x32_bf16 v[80:83], v[156:159], v[198:201], v[80:83]
	v_mfma_f32_16x16x32_bf16 v[68:71], v[148:151], v[206:209], v[68:71]
	v_mfma_f32_16x16x32_bf16 v[64:67], v[156:159], v[206:209], v[64:67]
	s_setprio 0
	s_add_i32 s8, s65, s68
	v_lshl_add_u64 v[178:179], s[40:41], 0, v[184:185]
	s_mov_b32 m0, s8
	ds_read_b128 v[160:163], v232 offset:16384
	ds_read_b128 v[164:167], v232 offset:17408
	ds_read_b128 v[168:171], v232 offset:18432
	ds_read_b128 v[172:175], v232 offset:19456
	ds_read_b128 v[194:197], v232 offset:20480
	ds_read_b128 v[198:201], v232 offset:21504
	ds_read_b128 v[202:205], v232 offset:22528
	ds_read_b128 v[206:209], v232 offset:23552
	global_load_lds_dwordx4 v[178:179], off
	s_add_i32 m0, s8, 0x2000
	s_add_u32 s8, s40, 0x60000
	v_lshl_add_u64 v[210:211], s[40:41], 0, v[188:189]
	s_addc_u32 s9, s41, 0
	s_add_i32 s65, s66, s68
	global_load_lds_dwordx4 v[210:211], off
	v_lshl_add_u64 v[212:213], s[8:9], 0, v[184:185]
	s_mov_b32 m0, s65
	v_lshl_add_u64 v[220:221], s[50:51], 0, v[186:187]
	global_load_lds_dwordx4 v[212:213], off
	v_lshl_add_u64 v[212:213], s[8:9], 0, v[188:189]
	s_add_i32 m0, s65, 0x2000
	s_nop 0
	global_load_lds_dwordx4 v[212:213], off
	v_lshl_add_u64 v[212:213], s[50:51], 0, v[182:183]
	s_mov_b32 m0, s72
	s_nop 0
	global_load_lds_dwordx4 v[212:213], off
	s_mov_b32 m0, s73
	s_nop 0
	global_load_lds_dwordx4 v[220:221], off
	s_waitcnt vmcnt(8)
	s_waitcnt lgkmcnt(0)
	s_barrier
	s_setprio 1
	v_mfma_f32_16x16x32_bf16 v[60:63], v[88:91], v[160:163], 0
	v_mfma_f32_16x16x32_bf16 v[56:59], v[104:107], v[160:163], 0
	v_mfma_f32_16x16x32_bf16 v[44:47], v[88:91], v[168:171], 0
	v_mfma_f32_16x16x32_bf16 v[40:43], v[104:107], v[168:171], 0
	v_mfma_f32_16x16x32_bf16 v[28:31], v[88:91], v[194:197], 0
	v_mfma_f32_16x16x32_bf16 v[24:27], v[104:107], v[194:197], 0
	v_mfma_f32_16x16x32_bf16 v[12:15], v[88:91], v[202:205], 0
	v_mfma_f32_16x16x32_bf16 v[8:11], v[104:107], v[202:205], 0
	v_mfma_f32_16x16x32_bf16 v[60:63], v[92:95], v[164:167], v[60:63]
	v_mfma_f32_16x16x32_bf16 v[56:59], v[108:111], v[164:167], v[56:59]
	v_mfma_f32_16x16x32_bf16 v[44:47], v[92:95], v[172:175], v[44:47]
	v_mfma_f32_16x16x32_bf16 v[40:43], v[108:111], v[172:175], v[40:43]
	v_mfma_f32_16x16x32_bf16 v[28:31], v[92:95], v[198:201], v[28:31]
	v_mfma_f32_16x16x32_bf16 v[24:27], v[108:111], v[198:201], v[24:27]
	v_mfma_f32_16x16x32_bf16 v[12:15], v[92:95], v[206:209], v[12:15]
	v_mfma_f32_16x16x32_bf16 v[8:11], v[108:111], v[206:209], v[8:11]
	v_mfma_f32_16x16x32_bf16 v[52:55], v[144:147], v[160:163], 0
	v_mfma_f32_16x16x32_bf16 v[48:51], v[152:155], v[160:163], 0
	v_mfma_f32_16x16x32_bf16 v[36:39], v[144:147], v[168:171], 0
	v_mfma_f32_16x16x32_bf16 v[32:35], v[152:155], v[168:171], 0
	v_mfma_f32_16x16x32_bf16 v[20:23], v[144:147], v[194:197], 0
	v_mfma_f32_16x16x32_bf16 v[16:19], v[152:155], v[194:197], 0
	v_mfma_f32_16x16x32_bf16 v[4:7], v[144:147], v[202:205], 0
	v_mfma_f32_16x16x32_bf16 v[0:3], v[152:155], v[202:205], 0
	v_mfma_f32_16x16x32_bf16 v[52:55], v[148:151], v[164:167], v[52:55]
	v_mfma_f32_16x16x32_bf16 v[48:51], v[156:159], v[164:167], v[48:51]
	v_mfma_f32_16x16x32_bf16 v[36:39], v[148:151], v[172:175], v[36:39]
	v_mfma_f32_16x16x32_bf16 v[32:35], v[156:159], v[172:175], v[32:35]
	s_setprio 2
	s_barrier
	v_mfma_f32_16x16x32_bf16 v[20:23], v[148:151], v[198:201], v[20:23]
	v_mfma_f32_16x16x32_bf16 v[16:19], v[156:159], v[198:201], v[16:19]
	v_mfma_f32_16x16x32_bf16 v[4:7], v[148:151], v[206:209], v[4:7]
	v_mfma_f32_16x16x32_bf16 v[0:3], v[156:159], v[206:209], v[0:3]
	s_setprio 0
	s_add_i32 s65, 0, 0x18000
	s_add_i32 s66, 0, 0x1c000
	v_add_u32_e32 v108, s65, v228
	v_add_u32_e32 v156, s66, v228
	ds_read_b128 v[88:91], v108
	ds_read_b128 v[92:95], v108 offset:1024
	ds_read_b128 v[104:107], v108 offset:2048
	ds_read_b128 v[108:111], v108 offset:3072
	ds_read_b128 v[144:147], v156
	ds_read_b128 v[148:151], v156 offset:1024
	ds_read_b128 v[152:155], v156 offset:2048
	ds_read_b128 v[156:159], v156 offset:3072
	s_add_u32 s8, s50, 0x60000
	s_addc_u32 s9, s51, 0
	s_mov_b32 m0, s74
	v_lshl_add_u64 v[222:223], s[8:9], 0, v[182:183]
	ds_read_b128 v[160:163], v232 offset:32768
	ds_read_b128 v[164:167], v232 offset:33792
	ds_read_b128 v[168:171], v232 offset:34816
	ds_read_b128 v[172:175], v232 offset:35840
	ds_read_b128 v[194:197], v232 offset:36864
	ds_read_b128 v[198:201], v232 offset:37888
	ds_read_b128 v[202:205], v232 offset:38912
	ds_read_b128 v[206:209], v232 offset:39936
	global_load_lds_dwordx4 v[222:223], off
	v_lshl_add_u64 v[222:223], s[8:9], 0, v[186:187]
	s_mov_b32 m0, s75
	s_nop 0
	global_load_lds_dwordx4 v[222:223], off
	s_waitcnt vmcnt(8)
	s_waitcnt lgkmcnt(0)
	s_barrier
	s_setprio 1
	v_mfma_f32_16x16x32_bf16 v[140:143], v[88:91], v[160:163], v[140:143]
	v_mfma_f32_16x16x32_bf16 v[136:139], v[104:107], v[160:163], v[136:139]
	v_mfma_f32_16x16x32_bf16 v[124:127], v[88:91], v[168:171], v[124:127]
	v_mfma_f32_16x16x32_bf16 v[120:123], v[104:107], v[168:171], v[120:123]
	v_mfma_f32_16x16x32_bf16 v[100:103], v[88:91], v[194:197], v[100:103]
	v_mfma_f32_16x16x32_bf16 v[96:99], v[104:107], v[194:197], v[96:99]
	v_mfma_f32_16x16x32_bf16 v[76:79], v[88:91], v[202:205], v[76:79]
	v_mfma_f32_16x16x32_bf16 v[72:75], v[104:107], v[202:205], v[72:75]
	v_mfma_f32_16x16x32_bf16 v[140:143], v[92:95], v[164:167], v[140:143]
	v_mfma_f32_16x16x32_bf16 v[136:139], v[108:111], v[164:167], v[136:139]
	v_mfma_f32_16x16x32_bf16 v[124:127], v[92:95], v[172:175], v[124:127]
	v_mfma_f32_16x16x32_bf16 v[120:123], v[108:111], v[172:175], v[120:123]
	v_mfma_f32_16x16x32_bf16 v[100:103], v[92:95], v[198:201], v[100:103]
	v_mfma_f32_16x16x32_bf16 v[96:99], v[108:111], v[198:201], v[96:99]
	v_mfma_f32_16x16x32_bf16 v[76:79], v[92:95], v[206:209], v[76:79]
	v_mfma_f32_16x16x32_bf16 v[72:75], v[108:111], v[206:209], v[72:75]
	v_mfma_f32_16x16x32_bf16 v[132:135], v[144:147], v[160:163], v[132:135]
	v_mfma_f32_16x16x32_bf16 v[128:131], v[152:155], v[160:163], v[128:131]
	v_mfma_f32_16x16x32_bf16 v[116:119], v[144:147], v[168:171], v[116:119]
	v_mfma_f32_16x16x32_bf16 v[112:115], v[152:155], v[168:171], v[112:115]
	v_mfma_f32_16x16x32_bf16 v[84:87], v[144:147], v[194:197], v[84:87]
	v_mfma_f32_16x16x32_bf16 v[80:83], v[152:155], v[194:197], v[80:83]
	v_mfma_f32_16x16x32_bf16 v[68:71], v[144:147], v[202:205], v[68:71]
	v_mfma_f32_16x16x32_bf16 v[64:67], v[152:155], v[202:205], v[64:67]
	v_mfma_f32_16x16x32_bf16 v[132:135], v[148:151], v[164:167], v[132:135]
	v_mfma_f32_16x16x32_bf16 v[128:131], v[156:159], v[164:167], v[128:131]
	v_mfma_f32_16x16x32_bf16 v[116:119], v[148:151], v[172:175], v[116:119]
	v_mfma_f32_16x16x32_bf16 v[112:115], v[156:159], v[172:175], v[112:115]
	s_setprio 2
	s_barrier
	v_mfma_f32_16x16x32_bf16 v[84:87], v[148:151], v[198:201], v[84:87]
	v_mfma_f32_16x16x32_bf16 v[80:83], v[156:159], v[198:201], v[80:83]
	v_mfma_f32_16x16x32_bf16 v[68:71], v[148:151], v[206:209], v[68:71]
	v_mfma_f32_16x16x32_bf16 v[64:67], v[156:159], v[206:209], v[64:67]
	s_setprio 0
	s_add_i32 s8, s65, s68
	v_lshl_add_u64 v[178:179], v[178:179], 0, s[34:35]
	s_mov_b32 m0, s8
	ds_read_b128 v[160:163], v232 offset:49152
	ds_read_b128 v[164:167], v232 offset:50176
	ds_read_b128 v[168:171], v232 offset:51200
	ds_read_b128 v[172:175], v232 offset:52224
	ds_read_b128 v[194:197], v232 offset:53248
	ds_read_b128 v[198:201], v232 offset:54272
	ds_read_b128 v[202:205], v232 offset:55296
	ds_read_b128 v[206:209], v232 offset:56320
	global_load_lds_dwordx4 v[178:179], off
	s_add_i32 m0, s8, 0x2000
	s_add_u32 s8, s40, 0x60080
	v_lshl_add_u64 v[178:179], v[210:211], 0, s[34:35]
	s_addc_u32 s9, s41, 0
	s_add_i32 s40, s66, s68
	global_load_lds_dwordx4 v[178:179], off
	v_lshl_add_u64 v[178:179], s[8:9], 0, v[184:185]
	s_mov_b32 m0, s40
	s_nop 0
	global_load_lds_dwordx4 v[178:179], off
	v_lshl_add_u64 v[178:179], s[8:9], 0, v[188:189]
	s_add_i32 m0, s40, 0x2000
	s_nop 0
	global_load_lds_dwordx4 v[178:179], off
	v_lshl_add_u64 v[178:179], v[212:213], 0, s[34:35]
	s_mov_b32 m0, s81
	s_nop 0
	global_load_lds_dwordx4 v[178:179], off
	v_lshl_add_u64 v[178:179], v[220:221], 0, s[34:35]
	s_mov_b32 m0, s82
	s_nop 0
	global_load_lds_dwordx4 v[178:179], off
	s_waitcnt vmcnt(8)
	s_waitcnt lgkmcnt(0)
	s_barrier
	s_setprio 1
	v_mfma_f32_16x16x32_bf16 v[60:63], v[88:91], v[160:163], v[60:63]
	v_mfma_f32_16x16x32_bf16 v[56:59], v[104:107], v[160:163], v[56:59]
	v_mfma_f32_16x16x32_bf16 v[44:47], v[88:91], v[168:171], v[44:47]
	v_mfma_f32_16x16x32_bf16 v[40:43], v[104:107], v[168:171], v[40:43]
	v_mfma_f32_16x16x32_bf16 v[28:31], v[88:91], v[194:197], v[28:31]
	v_mfma_f32_16x16x32_bf16 v[24:27], v[104:107], v[194:197], v[24:27]
	v_mfma_f32_16x16x32_bf16 v[12:15], v[88:91], v[202:205], v[12:15]
	v_mfma_f32_16x16x32_bf16 v[8:11], v[104:107], v[202:205], v[8:11]
	v_mfma_f32_16x16x32_bf16 v[60:63], v[92:95], v[164:167], v[60:63]
	v_mfma_f32_16x16x32_bf16 v[56:59], v[108:111], v[164:167], v[56:59]
	v_mfma_f32_16x16x32_bf16 v[44:47], v[92:95], v[172:175], v[44:47]
	v_mfma_f32_16x16x32_bf16 v[40:43], v[108:111], v[172:175], v[40:43]
	v_mfma_f32_16x16x32_bf16 v[28:31], v[92:95], v[198:201], v[28:31]
	v_mfma_f32_16x16x32_bf16 v[24:27], v[108:111], v[198:201], v[24:27]
	v_mfma_f32_16x16x32_bf16 v[12:15], v[92:95], v[206:209], v[12:15]
	v_mfma_f32_16x16x32_bf16 v[8:11], v[108:111], v[206:209], v[8:11]
	v_mfma_f32_16x16x32_bf16 v[52:55], v[144:147], v[160:163], v[52:55]
	v_mfma_f32_16x16x32_bf16 v[48:51], v[152:155], v[160:163], v[48:51]
	v_mfma_f32_16x16x32_bf16 v[36:39], v[144:147], v[168:171], v[36:39]
	v_mfma_f32_16x16x32_bf16 v[32:35], v[152:155], v[168:171], v[32:35]
	v_mfma_f32_16x16x32_bf16 v[20:23], v[144:147], v[194:197], v[20:23]
	v_mfma_f32_16x16x32_bf16 v[16:19], v[152:155], v[194:197], v[16:19]
	v_mfma_f32_16x16x32_bf16 v[4:7], v[144:147], v[202:205], v[4:7]
	v_mfma_f32_16x16x32_bf16 v[0:3], v[152:155], v[202:205], v[0:3]
	v_mfma_f32_16x16x32_bf16 v[52:55], v[148:151], v[164:167], v[52:55]
	v_mfma_f32_16x16x32_bf16 v[48:51], v[156:159], v[164:167], v[48:51]
	v_mfma_f32_16x16x32_bf16 v[36:39], v[148:151], v[172:175], v[36:39]
	v_mfma_f32_16x16x32_bf16 v[32:35], v[156:159], v[172:175], v[32:35]
	s_setprio 2
	s_barrier
	v_mfma_f32_16x16x32_bf16 v[20:23], v[148:151], v[198:201], v[20:23]
	v_mfma_f32_16x16x32_bf16 v[16:19], v[156:159], v[198:201], v[16:19]
	v_mfma_f32_16x16x32_bf16 v[4:7], v[148:151], v[206:209], v[4:7]
	v_mfma_f32_16x16x32_bf16 v[0:3], v[156:159], v[206:209], v[0:3]
	s_setprio 0
	s_add_u32 s93, s93, 0x180
	s_addc_u32 s94, s94, 0
	s_cmp_ge_i32 s64, s63
	s_mov_b64 s[8:9], s[38:39]
	s_mov_b32 s40, s64
	s_cbranch_scc1 .Lpeel_exit_5

.Lpeel_exit_5:
	s_and_b64 vcc, exec, s[20:21]
	s_cbranch_vccz .LBB0_1049

.LBB0_1220:
	s_ashr_i32 s21, s20, 31
	s_lshl_b64 s[28:29], s[20:21], 19
	s_add_u32 s21, s54, s28
	s_addc_u32 s23, s55, s29
	s_ashr_i32 s27, s26, 31
	s_lshl_b64 s[38:39], s[26:27], 7
	s_add_u32 s28, s21, s38
	s_addc_u32 s29, s23, s39
	s_ashr_i32 s23, s22, 31
	s_lshl_b64 s[50:51], s[22:23], 19
	s_add_u32 s21, s58, s50
	s_addc_u32 s23, s59, s51
	s_add_u32 s38, s21, s38
	s_addc_u32 s39, s23, s39
	s_cmp_lt_i32 s52, 1
	s_cbranch_scc1 .LBB0_1227
	s_and_b64 s[50:51], s[24:25], exec
	s_cselect_b32 s21, s29, s43
	s_cselect_b32 s23, s28, s42
	s_cselect_b32 s27, s39, s5
	s_cselect_b32 s53, s38, s4
	s_add_i32 s63, s52, -2
	s_add_u32 s95, s4, 0x100
	s_addc_u32 vcc_lo, s5, 0
	s_add_u32 s4, s42, 0x40080
	s_addc_u32 s5, s43, 0
	s_mov_b32 s42, 0
	s_waitcnt vmcnt(0)
	s_add_i32 vcc_hi, s42, 2
	s_add_u32 s43, s4, 0xfffc0080
	s_addc_u32 s50, s5, -1
	s_add_i32 s64, 0, 0x10000
	s_cmp_eq_u32 s63, s42
	s_cselect_b32 s51, s21, s50
	s_cselect_b32 s50, s23, s43
	s_cselect_b32 s43, s27, vcc_lo
	s_cselect_b32 s42, s53, s95
	s_add_i32 s66, 0, 0x14000
	v_add_u32_e32 v108, s64, v228
	v_add_u32_e32 v156, s66, v228
	ds_read_b128 v[88:91], v108
	ds_read_b128 v[92:95], v108 offset:1024
	ds_read_b128 v[104:107], v108 offset:2048
	ds_read_b128 v[108:111], v108 offset:3072
	ds_read_b128 v[144:147], v156
	ds_read_b128 v[148:151], v156 offset:1024
	ds_read_b128 v[152:155], v156 offset:2048
	ds_read_b128 v[156:159], v156 offset:3072
	v_lshl_add_u64 v[178:179], s[4:5], 0, v[192:193]
	s_add_i32 m0, s7, 0xc000
	ds_read_b128 v[160:163], v232
	ds_read_b128 v[164:167], v232 offset:1024
	ds_read_b128 v[168:171], v232 offset:2048
	ds_read_b128 v[172:175], v232 offset:3072
	ds_read_b128 v[194:197], v232 offset:4096
	ds_read_b128 v[198:201], v232 offset:5120
	ds_read_b128 v[202:205], v232 offset:6144
	ds_read_b128 v[206:209], v232 offset:7168
	global_load_lds_dwordx4 v[178:179], off
	v_lshl_add_u64 v[178:179], s[4:5], 0, v[190:191]
	s_add_i32 m0, s7, 0xe000
	s_nop 0
	global_load_lds_dwordx4 v[178:179], off
	s_waitcnt vmcnt(8)
	s_waitcnt lgkmcnt(0)
	s_barrier
	s_setprio 1
	v_mfma_f32_16x16x32_bf16 v[140:143], v[88:91], v[160:163], 0
	v_mfma_f32_16x16x32_bf16 v[136:139], v[104:107], v[160:163], 0
	v_mfma_f32_16x16x32_bf16 v[124:127], v[88:91], v[168:171], 0
	v_mfma_f32_16x16x32_bf16 v[120:123], v[104:107], v[168:171], 0
	v_mfma_f32_16x16x32_bf16 v[100:103], v[88:91], v[194:197], 0
	v_mfma_f32_16x16x32_bf16 v[96:99], v[104:107], v[194:197], 0
	v_mfma_f32_16x16x32_bf16 v[76:79], v[88:91], v[202:205], 0
	v_mfma_f32_16x16x32_bf16 v[72:75], v[104:107], v[202:205], 0
	v_mfma_f32_16x16x32_bf16 v[140:143], v[92:95], v[164:167], v[140:143]
	v_mfma_f32_16x16x32_bf16 v[136:139], v[108:111], v[164:167], v[136:139]
	v_mfma_f32_16x16x32_bf16 v[124:127], v[92:95], v[172:175], v[124:127]
	v_mfma_f32_16x16x32_bf16 v[120:123], v[108:111], v[172:175], v[120:123]
	v_mfma_f32_16x16x32_bf16 v[100:103], v[92:95], v[198:201], v[100:103]
	v_mfma_f32_16x16x32_bf16 v[96:99], v[108:111], v[198:201], v[96:99]
	v_mfma_f32_16x16x32_bf16 v[76:79], v[92:95], v[206:209], v[76:79]
	v_mfma_f32_16x16x32_bf16 v[72:75], v[108:111], v[206:209], v[72:75]
	v_mfma_f32_16x16x32_bf16 v[132:135], v[144:147], v[160:163], 0
	v_mfma_f32_16x16x32_bf16 v[128:131], v[152:155], v[160:163], 0
	v_mfma_f32_16x16x32_bf16 v[116:119], v[144:147], v[168:171], 0
	v_mfma_f32_16x16x32_bf16 v[112:115], v[152:155], v[168:171], 0
	v_mfma_f32_16x16x32_bf16 v[84:87], v[144:147], v[194:197], 0
	v_mfma_f32_16x16x32_bf16 v[80:83], v[152:155], v[194:197], 0
	v_mfma_f32_16x16x32_bf16 v[68:71], v[144:147], v[202:205], 0
	v_mfma_f32_16x16x32_bf16 v[64:67], v[152:155], v[202:205], 0
	v_mfma_f32_16x16x32_bf16 v[132:135], v[148:151], v[164:167], v[132:135]
	v_mfma_f32_16x16x32_bf16 v[128:131], v[156:159], v[164:167], v[128:131]
	v_mfma_f32_16x16x32_bf16 v[116:119], v[148:151], v[172:175], v[116:119]
	v_mfma_f32_16x16x32_bf16 v[112:115], v[156:159], v[172:175], v[112:115]
	s_setprio 2
	s_barrier
	v_mfma_f32_16x16x32_bf16 v[84:87], v[148:151], v[198:201], v[84:87]
	v_mfma_f32_16x16x32_bf16 v[80:83], v[156:159], v[198:201], v[80:83]
	v_mfma_f32_16x16x32_bf16 v[68:71], v[148:151], v[206:209], v[68:71]
	v_mfma_f32_16x16x32_bf16 v[64:67], v[156:159], v[206:209], v[64:67]
	s_setprio 0
	s_add_i32 s64, s64, s72
	v_lshl_add_u64 v[178:179], s[42:43], 0, v[184:185]
	s_mov_b32 m0, s64
	ds_read_b128 v[160:163], v232 offset:16384
	ds_read_b128 v[164:167], v232 offset:17408
	ds_read_b128 v[168:171], v232 offset:18432
	ds_read_b128 v[172:175], v232 offset:19456
	ds_read_b128 v[194:197], v232 offset:20480
	ds_read_b128 v[198:201], v232 offset:21504
	ds_read_b128 v[202:205], v232 offset:22528
	ds_read_b128 v[206:209], v232 offset:23552
	global_load_lds_dwordx4 v[178:179], off
	s_add_i32 m0, s64, 0x2000
	s_add_u32 s64, s42, 0x40000
	v_lshl_add_u64 v[210:211], s[42:43], 0, v[188:189]
	s_addc_u32 s65, s43, 0
	s_add_i32 s66, s66, s72
	global_load_lds_dwordx4 v[210:211], off
	v_lshl_add_u64 v[212:213], s[64:65], 0, v[184:185]
	s_mov_b32 m0, s66
	v_lshl_add_u64 v[220:221], s[50:51], 0, v[186:187]
	global_load_lds_dwordx4 v[212:213], off
	v_lshl_add_u64 v[212:213], s[64:65], 0, v[188:189]
	s_add_i32 m0, s66, 0x2000
	s_nop 0
	global_load_lds_dwordx4 v[212:213], off
	v_lshl_add_u64 v[212:213], s[50:51], 0, v[182:183]
	s_mov_b32 m0, s7
	s_nop 0
	global_load_lds_dwordx4 v[212:213], off
	s_mov_b32 m0, s73
	s_nop 0
	global_load_lds_dwordx4 v[220:221], off
	s_waitcnt vmcnt(8)
	s_waitcnt lgkmcnt(0)
	s_barrier
	s_setprio 1
	v_mfma_f32_16x16x32_bf16 v[60:63], v[88:91], v[160:163], 0
	v_mfma_f32_16x16x32_bf16 v[56:59], v[104:107], v[160:163], 0
	v_mfma_f32_16x16x32_bf16 v[44:47], v[88:91], v[168:171], 0
	v_mfma_f32_16x16x32_bf16 v[40:43], v[104:107], v[168:171], 0
	v_mfma_f32_16x16x32_bf16 v[28:31], v[88:91], v[194:197], 0
	v_mfma_f32_16x16x32_bf16 v[24:27], v[104:107], v[194:197], 0
	v_mfma_f32_16x16x32_bf16 v[12:15], v[88:91], v[202:205], 0
	v_mfma_f32_16x16x32_bf16 v[8:11], v[104:107], v[202:205], 0
	v_mfma_f32_16x16x32_bf16 v[60:63], v[92:95], v[164:167], v[60:63]
	v_mfma_f32_16x16x32_bf16 v[56:59], v[108:111], v[164:167], v[56:59]
	v_mfma_f32_16x16x32_bf16 v[44:47], v[92:95], v[172:175], v[44:47]
	v_mfma_f32_16x16x32_bf16 v[40:43], v[108:111], v[172:175], v[40:43]
	v_mfma_f32_16x16x32_bf16 v[28:31], v[92:95], v[198:201], v[28:31]
	v_mfma_f32_16x16x32_bf16 v[24:27], v[108:111], v[198:201], v[24:27]
	v_mfma_f32_16x16x32_bf16 v[12:15], v[92:95], v[206:209], v[12:15]
	v_mfma_f32_16x16x32_bf16 v[8:11], v[108:111], v[206:209], v[8:11]
	v_mfma_f32_16x16x32_bf16 v[52:55], v[144:147], v[160:163], 0
	v_mfma_f32_16x16x32_bf16 v[48:51], v[152:155], v[160:163], 0
	v_mfma_f32_16x16x32_bf16 v[36:39], v[144:147], v[168:171], 0
	v_mfma_f32_16x16x32_bf16 v[32:35], v[152:155], v[168:171], 0
	v_mfma_f32_16x16x32_bf16 v[20:23], v[144:147], v[194:197], 0
	v_mfma_f32_16x16x32_bf16 v[16:19], v[152:155], v[194:197], 0
	v_mfma_f32_16x16x32_bf16 v[4:7], v[144:147], v[202:205], 0
	v_mfma_f32_16x16x32_bf16 v[0:3], v[152:155], v[202:205], 0
	v_mfma_f32_16x16x32_bf16 v[52:55], v[148:151], v[164:167], v[52:55]
	v_mfma_f32_16x16x32_bf16 v[48:51], v[156:159], v[164:167], v[48:51]
	v_mfma_f32_16x16x32_bf16 v[36:39], v[148:151], v[172:175], v[36:39]
	v_mfma_f32_16x16x32_bf16 v[32:35], v[156:159], v[172:175], v[32:35]
	s_setprio 2
	s_barrier
	v_mfma_f32_16x16x32_bf16 v[20:23], v[148:151], v[198:201], v[20:23]
	v_mfma_f32_16x16x32_bf16 v[16:19], v[156:159], v[198:201], v[16:19]
	v_mfma_f32_16x16x32_bf16 v[4:7], v[148:151], v[206:209], v[4:7]
	v_mfma_f32_16x16x32_bf16 v[0:3], v[156:159], v[206:209], v[0:3]
	s_setprio 0
	s_add_i32 s64, 0, 0x18000
	s_add_i32 s65, 0, 0x1c000
	v_add_u32_e32 v108, s64, v228
	v_add_u32_e32 v156, s65, v228
	ds_read_b128 v[88:91], v108
	ds_read_b128 v[92:95], v108 offset:1024
	ds_read_b128 v[104:107], v108 offset:2048
	ds_read_b128 v[108:111], v108 offset:3072
	ds_read_b128 v[144:147], v156
	ds_read_b128 v[148:151], v156 offset:1024
	ds_read_b128 v[152:155], v156 offset:2048
	ds_read_b128 v[156:159], v156 offset:3072
	s_add_u32 s50, s50, 0x40000
	s_addc_u32 s51, s51, 0
	s_mov_b32 m0, s74
	v_lshl_add_u64 v[222:223], s[50:51], 0, v[182:183]
	ds_read_b128 v[160:163], v232 offset:32768
	ds_read_b128 v[164:167], v232 offset:33792
	ds_read_b128 v[168:171], v232 offset:34816
	ds_read_b128 v[172:175], v232 offset:35840
	ds_read_b128 v[194:197], v232 offset:36864
	ds_read_b128 v[198:201], v232 offset:37888
	ds_read_b128 v[202:205], v232 offset:38912
	ds_read_b128 v[206:209], v232 offset:39936
	global_load_lds_dwordx4 v[222:223], off
	v_lshl_add_u64 v[222:223], s[50:51], 0, v[186:187]
	s_mov_b32 m0, s75
	s_nop 0
	global_load_lds_dwordx4 v[222:223], off
	s_waitcnt vmcnt(8)
	s_waitcnt lgkmcnt(0)
	s_barrier
	s_setprio 1
	v_mfma_f32_16x16x32_bf16 v[140:143], v[88:91], v[160:163], v[140:143]
	v_mfma_f32_16x16x32_bf16 v[136:139], v[104:107], v[160:163], v[136:139]
	v_mfma_f32_16x16x32_bf16 v[124:127], v[88:91], v[168:171], v[124:127]
	v_mfma_f32_16x16x32_bf16 v[120:123], v[104:107], v[168:171], v[120:123]
	v_mfma_f32_16x16x32_bf16 v[100:103], v[88:91], v[194:197], v[100:103]
	v_mfma_f32_16x16x32_bf16 v[96:99], v[104:107], v[194:197], v[96:99]
	v_mfma_f32_16x16x32_bf16 v[76:79], v[88:91], v[202:205], v[76:79]
	v_mfma_f32_16x16x32_bf16 v[72:75], v[104:107], v[202:205], v[72:75]
	v_mfma_f32_16x16x32_bf16 v[140:143], v[92:95], v[164:167], v[140:143]
	v_mfma_f32_16x16x32_bf16 v[136:139], v[108:111], v[164:167], v[136:139]
	v_mfma_f32_16x16x32_bf16 v[124:127], v[92:95], v[172:175], v[124:127]
	v_mfma_f32_16x16x32_bf16 v[120:123], v[108:111], v[172:175], v[120:123]
	v_mfma_f32_16x16x32_bf16 v[100:103], v[92:95], v[198:201], v[100:103]
	v_mfma_f32_16x16x32_bf16 v[96:99], v[108:111], v[198:201], v[96:99]
	v_mfma_f32_16x16x32_bf16 v[76:79], v[92:95], v[206:209], v[76:79]
	v_mfma_f32_16x16x32_bf16 v[72:75], v[108:111], v[206:209], v[72:75]
	v_mfma_f32_16x16x32_bf16 v[132:135], v[144:147], v[160:163], v[132:135]
	v_mfma_f32_16x16x32_bf16 v[128:131], v[152:155], v[160:163], v[128:131]
	v_mfma_f32_16x16x32_bf16 v[116:119], v[144:147], v[168:171], v[116:119]
	v_mfma_f32_16x16x32_bf16 v[112:115], v[152:155], v[168:171], v[112:115]
	v_mfma_f32_16x16x32_bf16 v[84:87], v[144:147], v[194:197], v[84:87]
	v_mfma_f32_16x16x32_bf16 v[80:83], v[152:155], v[194:197], v[80:83]
	v_mfma_f32_16x16x32_bf16 v[68:71], v[144:147], v[202:205], v[68:71]
	v_mfma_f32_16x16x32_bf16 v[64:67], v[152:155], v[202:205], v[64:67]
	v_mfma_f32_16x16x32_bf16 v[132:135], v[148:151], v[164:167], v[132:135]
	v_mfma_f32_16x16x32_bf16 v[128:131], v[156:159], v[164:167], v[128:131]
	v_mfma_f32_16x16x32_bf16 v[116:119], v[148:151], v[172:175], v[116:119]
	v_mfma_f32_16x16x32_bf16 v[112:115], v[156:159], v[172:175], v[112:115]
	s_setprio 2
	s_barrier
	v_mfma_f32_16x16x32_bf16 v[84:87], v[148:151], v[198:201], v[84:87]
	v_mfma_f32_16x16x32_bf16 v[80:83], v[156:159], v[198:201], v[80:83]
	v_mfma_f32_16x16x32_bf16 v[68:71], v[148:151], v[206:209], v[68:71]
	v_mfma_f32_16x16x32_bf16 v[64:67], v[156:159], v[206:209], v[64:67]
	s_setprio 0
	s_add_i32 s50, s64, s72
	v_lshl_add_u64 v[178:179], v[178:179], 0, s[34:35]
	s_mov_b32 m0, s50
	ds_read_b128 v[160:163], v232 offset:49152
	ds_read_b128 v[164:167], v232 offset:50176
	ds_read_b128 v[168:171], v232 offset:51200
	ds_read_b128 v[172:175], v232 offset:52224
	ds_read_b128 v[194:197], v232 offset:53248
	ds_read_b128 v[198:201], v232 offset:54272
	ds_read_b128 v[202:205], v232 offset:55296
	ds_read_b128 v[206:209], v232 offset:56320
	global_load_lds_dwordx4 v[178:179], off
	s_add_i32 m0, s50, 0x2000
	s_add_u32 s42, s42, 0x40080
	v_lshl_add_u64 v[178:179], v[210:211], 0, s[34:35]
	s_addc_u32 s43, s43, 0
	s_add_i32 s50, s65, s72
	global_load_lds_dwordx4 v[178:179], off
	v_lshl_add_u64 v[178:179], s[42:43], 0, v[184:185]
	s_mov_b32 m0, s50
	s_nop 0
	global_load_lds_dwordx4 v[178:179], off
	v_lshl_add_u64 v[178:179], s[42:43], 0, v[188:189]
	s_add_i32 m0, s50, 0x2000
	s_nop 0
	global_load_lds_dwordx4 v[178:179], off
	v_lshl_add_u64 v[178:179], v[212:213], 0, s[34:35]
	s_mov_b32 m0, s81
	s_nop 0
	global_load_lds_dwordx4 v[178:179], off
	v_lshl_add_u64 v[178:179], v[220:221], 0, s[34:35]
	s_mov_b32 m0, s82
	s_nop 0
	global_load_lds_dwordx4 v[178:179], off
	s_waitcnt vmcnt(8)
	s_waitcnt lgkmcnt(0)
	s_barrier
	s_setprio 1
	v_mfma_f32_16x16x32_bf16 v[60:63], v[88:91], v[160:163], v[60:63]
	v_mfma_f32_16x16x32_bf16 v[56:59], v[104:107], v[160:163], v[56:59]
	v_mfma_f32_16x16x32_bf16 v[44:47], v[88:91], v[168:171], v[44:47]
	v_mfma_f32_16x16x32_bf16 v[40:43], v[104:107], v[168:171], v[40:43]
	v_mfma_f32_16x16x32_bf16 v[28:31], v[88:91], v[194:197], v[28:31]
	v_mfma_f32_16x16x32_bf16 v[24:27], v[104:107], v[194:197], v[24:27]
	v_mfma_f32_16x16x32_bf16 v[12:15], v[88:91], v[202:205], v[12:15]
	v_mfma_f32_16x16x32_bf16 v[8:11], v[104:107], v[202:205], v[8:11]
	v_mfma_f32_16x16x32_bf16 v[60:63], v[92:95], v[164:167], v[60:63]
	v_mfma_f32_16x16x32_bf16 v[56:59], v[108:111], v[164:167], v[56:59]
	v_mfma_f32_16x16x32_bf16 v[44:47], v[92:95], v[172:175], v[44:47]
	v_mfma_f32_16x16x32_bf16 v[40:43], v[108:111], v[172:175], v[40:43]
	v_mfma_f32_16x16x32_bf16 v[28:31], v[92:95], v[198:201], v[28:31]
	v_mfma_f32_16x16x32_bf16 v[24:27], v[108:111], v[198:201], v[24:27]
	v_mfma_f32_16x16x32_bf16 v[12:15], v[92:95], v[206:209], v[12:15]
	v_mfma_f32_16x16x32_bf16 v[8:11], v[108:111], v[206:209], v[8:11]
	v_mfma_f32_16x16x32_bf16 v[52:55], v[144:147], v[160:163], v[52:55]
	v_mfma_f32_16x16x32_bf16 v[48:51], v[152:155], v[160:163], v[48:51]
	v_mfma_f32_16x16x32_bf16 v[36:39], v[144:147], v[168:171], v[36:39]
	v_mfma_f32_16x16x32_bf16 v[32:35], v[152:155], v[168:171], v[32:35]
	v_mfma_f32_16x16x32_bf16 v[20:23], v[144:147], v[194:197], v[20:23]
	v_mfma_f32_16x16x32_bf16 v[16:19], v[152:155], v[194:197], v[16:19]
	v_mfma_f32_16x16x32_bf16 v[4:7], v[144:147], v[202:205], v[4:7]
	v_mfma_f32_16x16x32_bf16 v[0:3], v[152:155], v[202:205], v[0:3]
	v_mfma_f32_16x16x32_bf16 v[52:55], v[148:151], v[164:167], v[52:55]
	v_mfma_f32_16x16x32_bf16 v[48:51], v[156:159], v[164:167], v[48:51]
	v_mfma_f32_16x16x32_bf16 v[36:39], v[148:151], v[172:175], v[36:39]
	v_mfma_f32_16x16x32_bf16 v[32:35], v[156:159], v[172:175], v[32:35]
	s_setprio 2
	s_barrier
	v_mfma_f32_16x16x32_bf16 v[20:23], v[148:151], v[198:201], v[20:23]
	v_mfma_f32_16x16x32_bf16 v[16:19], v[156:159], v[198:201], v[16:19]
	v_mfma_f32_16x16x32_bf16 v[4:7], v[148:151], v[206:209], v[4:7]
	v_mfma_f32_16x16x32_bf16 v[0:3], v[156:159], v[206:209], v[0:3]
	s_setprio 0
	s_add_u32 s95, s95, 0x100
	s_addc_u32 vcc_lo, vcc_lo, 0
	s_add_u32 s4, s4, 0x100
	s_addc_u32 s5, s5, 0
	s_cmp_ge_i32 vcc_hi, s52
	s_mov_b32 s42, vcc_hi
	s_cbranch_scc1 .Lpeel_exit_6

.Lpeel_exit_6:
	s_and_b64 vcc, exec, s[16:17]
	s_cbranch_vccz .LBB0_1225
